# GEMM main loops: removed the lgkmcnt(8) pacing wait in front of the first barrier of the two fragment-load phases
# baseline (speedup 1.0000x reference)
.LBB0_100:
	s_add_u32 s21, s48, 0xfff00080
	s_addc_u32 s28, s49, -1
	s_add_i32 s60, 0, 0x10000
	v_add_u32_e32 v124, s60, v175
	ds_read_b128 v[112:115], v124
	ds_read_b128 v[116:119], v124 offset:1024
	ds_read_b128 v[120:123], v124 offset:2048
	ds_read_b128 v[124:127], v124 offset:3072
	s_cmp_eq_u32 s20, 60
	s_cselect_b32 s51, s43, s28
	s_cselect_b32 s50, s24, s21
	s_cselect_b32 s29, s1, vcc_hi
	s_cselect_b32 s28, s25, vcc_lo
	v_lshl_add_u64 v[184:185], s[48:49], 0, v[158:159]
	s_add_i32 m0, s55, 0xc000
	ds_read_b128 v[128:131], v199
	ds_read_b128 v[132:135], v199 offset:1024
	ds_read_b128 v[162:165], v199 offset:2048
	ds_read_b128 v[166:169], v199 offset:3072
	ds_read_b128 v[170:173], v199 offset:4096
	ds_read_b128 v[200:203], v199 offset:5120
	ds_read_b128 v[204:207], v199 offset:6144
	ds_read_b128 v[208:211], v199 offset:7168
	global_load_lds_dwordx4 v[184:185], off
	v_lshl_add_u64 v[184:185], s[48:49], 0, v[160:161]
	s_add_i32 m0, s55, 0xe000
	s_nop 0
	global_load_lds_dwordx4 v[184:185], off
	s_barrier
	s_waitcnt lgkmcnt(0)
	v_mfma_f32_16x16x32_bf16 v[148:151], v[112:115], v[128:131], v[148:151]
	v_mfma_f32_16x16x32_bf16 v[144:147], v[120:123], v[128:131], v[144:147]
	v_mfma_f32_16x16x32_bf16 v[108:111], v[112:115], v[162:165], v[108:111]
	v_mfma_f32_16x16x32_bf16 v[104:107], v[120:123], v[162:165], v[104:107]
	v_mfma_f32_16x16x32_bf16 v[92:95], v[112:115], v[170:173], v[92:95]
	v_mfma_f32_16x16x32_bf16 v[88:91], v[120:123], v[170:173], v[88:91]
	v_mfma_f32_16x16x32_bf16 v[76:79], v[112:115], v[204:207], v[76:79]
	v_mfma_f32_16x16x32_bf16 v[72:75], v[120:123], v[204:207], v[72:75]
	v_mfma_f32_16x16x32_bf16 v[148:151], v[116:119], v[132:135], v[148:151]
	v_mfma_f32_16x16x32_bf16 v[144:147], v[124:127], v[132:135], v[144:147]
	v_mfma_f32_16x16x32_bf16 v[108:111], v[116:119], v[166:169], v[108:111]
	v_mfma_f32_16x16x32_bf16 v[104:107], v[124:127], v[166:169], v[104:107]
	v_mfma_f32_16x16x32_bf16 v[92:95], v[116:119], v[200:203], v[92:95]
	v_mfma_f32_16x16x32_bf16 v[88:91], v[124:127], v[200:203], v[88:91]
	v_mfma_f32_16x16x32_bf16 v[76:79], v[116:119], v[208:211], v[76:79]
	v_mfma_f32_16x16x32_bf16 v[72:75], v[124:127], v[208:211], v[72:75]
	s_barrier
	s_add_i32 s21, 0, 0x14000
	v_add_u32_e32 v184, s21, v175
	s_add_i32 s60, s60, s54
	ds_read_b128 v[212:215], v184
	ds_read_b128 v[216:219], v184 offset:1024
	ds_read_b128 v[232:235], v184 offset:2048
	ds_read_b128 v[236:239], v184 offset:3072
	v_lshl_add_u64 v[184:185], s[28:29], 0, v[176:177]
	s_mov_b32 m0, s60
	v_lshl_add_u64 v[192:193], s[28:29], 0, v[152:153]
	global_load_lds_dwordx4 v[184:185], off
	s_add_i32 m0, s60, 0x2000
	s_nop 0
	global_load_lds_dwordx4 v[192:193], off
	s_barrier
	s_waitcnt lgkmcnt(0)
	v_mfma_f32_16x16x32_bf16 v[140:143], v[212:215], v[128:131], v[140:143]
	v_mfma_f32_16x16x32_bf16 v[100:103], v[212:215], v[162:165], v[100:103]
	v_mfma_f32_16x16x32_bf16 v[96:99], v[232:235], v[162:165], v[96:99]
	v_mfma_f32_16x16x32_bf16 v[84:87], v[212:215], v[170:173], v[84:87]
	v_mfma_f32_16x16x32_bf16 v[80:83], v[232:235], v[170:173], v[80:83]
	v_mfma_f32_16x16x32_bf16 v[68:71], v[212:215], v[204:207], v[68:71]
	v_mfma_f32_16x16x32_bf16 v[64:67], v[232:235], v[204:207], v[64:67]
	v_mfma_f32_16x16x32_bf16 v[140:143], v[216:219], v[132:135], v[140:143]
	v_mfma_f32_16x16x32_bf16 v[128:131], v[232:235], v[128:131], v[136:139]
	v_mfma_f32_16x16x32_bf16 v[100:103], v[216:219], v[166:169], v[100:103]
	v_mfma_f32_16x16x32_bf16 v[96:99], v[236:239], v[166:169], v[96:99]
	v_mfma_f32_16x16x32_bf16 v[84:87], v[216:219], v[200:203], v[84:87]
	v_mfma_f32_16x16x32_bf16 v[80:83], v[236:239], v[200:203], v[80:83]
	v_mfma_f32_16x16x32_bf16 v[68:71], v[216:219], v[208:211], v[68:71]
	v_mfma_f32_16x16x32_bf16 v[64:67], v[236:239], v[208:211], v[64:67]
	v_mfma_f32_16x16x32_bf16 v[128:131], v[236:239], v[132:135], v[128:131]
	s_mov_b32 m0, s55
	v_lshl_add_u64 v[194:195], s[50:51], 0, v[156:157]
	s_barrier
	ds_read_b128 v[132:135], v199 offset:16384
	ds_read_b128 v[136:139], v199 offset:17408
	ds_read_b128 v[162:165], v199 offset:18432
	ds_read_b128 v[166:169], v199 offset:19456
	ds_read_b128 v[170:173], v199 offset:20480
	ds_read_b128 v[200:203], v199 offset:21504
	ds_read_b128 v[204:207], v199 offset:22528
	ds_read_b128 v[208:211], v199 offset:23552
	global_load_lds_dwordx4 v[194:195], off
	v_lshl_add_u64 v[240:241], s[50:51], 0, v[154:155]
	s_mov_b32 m0, s56
	s_nop 0
	global_load_lds_dwordx4 v[240:241], off
	s_barrier
	s_waitcnt lgkmcnt(0)
	v_mfma_f32_16x16x32_bf16 v[60:63], v[112:115], v[132:135], v[60:63]
	v_mfma_f32_16x16x32_bf16 v[56:59], v[120:123], v[132:135], v[56:59]
	v_mfma_f32_16x16x32_bf16 v[44:47], v[112:115], v[162:165], v[44:47]
	v_mfma_f32_16x16x32_bf16 v[40:43], v[120:123], v[162:165], v[40:43]
	v_mfma_f32_16x16x32_bf16 v[28:31], v[112:115], v[170:173], v[28:31]
	v_mfma_f32_16x16x32_bf16 v[24:27], v[120:123], v[170:173], v[24:27]
	v_mfma_f32_16x16x32_bf16 v[12:15], v[112:115], v[204:207], v[12:15]
	v_mfma_f32_16x16x32_bf16 v[8:11], v[120:123], v[204:207], v[8:11]
	v_mfma_f32_16x16x32_bf16 v[60:63], v[116:119], v[136:139], v[60:63]
	v_mfma_f32_16x16x32_bf16 v[56:59], v[124:127], v[136:139], v[56:59]
	v_mfma_f32_16x16x32_bf16 v[44:47], v[116:119], v[166:169], v[44:47]
	v_mfma_f32_16x16x32_bf16 v[40:43], v[124:127], v[166:169], v[40:43]
	v_mfma_f32_16x16x32_bf16 v[28:31], v[116:119], v[200:203], v[28:31]
	v_mfma_f32_16x16x32_bf16 v[24:27], v[124:127], v[200:203], v[24:27]
	v_mfma_f32_16x16x32_bf16 v[12:15], v[116:119], v[208:211], v[12:15]
	v_mfma_f32_16x16x32_bf16 v[8:11], v[124:127], v[208:211], v[8:11]
	s_barrier
	s_add_u32 s60, s28, 0x100000
	s_addc_u32 s61, s29, 0
	s_add_i32 s21, s21, s54
	v_lshl_add_u64 v[112:113], s[60:61], 0, v[176:177]
	s_mov_b32 m0, s21
	s_nop 0
	global_load_lds_dwordx4 v[112:113], off
	v_lshl_add_u64 v[112:113], s[60:61], 0, v[152:153]
	s_add_i32 m0, s21, 0x2000
	s_nop 0
	global_load_lds_dwordx4 v[112:113], off
	s_waitcnt vmcnt(6)
	s_barrier
	v_mfma_f32_16x16x32_bf16 v[52:55], v[212:215], v[132:135], v[52:55]
	v_mfma_f32_16x16x32_bf16 v[48:51], v[232:235], v[132:135], v[48:51]
	v_mfma_f32_16x16x32_bf16 v[36:39], v[212:215], v[162:165], v[36:39]
	v_mfma_f32_16x16x32_bf16 v[32:35], v[232:235], v[162:165], v[32:35]
	v_mfma_f32_16x16x32_bf16 v[20:23], v[212:215], v[170:173], v[20:23]
	v_mfma_f32_16x16x32_bf16 v[16:19], v[232:235], v[170:173], v[16:19]
	v_mfma_f32_16x16x32_bf16 v[4:7], v[212:215], v[204:207], v[4:7]
	v_mfma_f32_16x16x32_bf16 v[0:3], v[232:235], v[204:207], v[0:3]
	v_mfma_f32_16x16x32_bf16 v[52:55], v[216:219], v[136:139], v[52:55]
	v_mfma_f32_16x16x32_bf16 v[48:51], v[236:239], v[136:139], v[48:51]
	v_mfma_f32_16x16x32_bf16 v[36:39], v[216:219], v[166:169], v[36:39]
	v_mfma_f32_16x16x32_bf16 v[32:35], v[236:239], v[166:169], v[32:35]
	v_mfma_f32_16x16x32_bf16 v[20:23], v[216:219], v[200:203], v[20:23]
	v_mfma_f32_16x16x32_bf16 v[16:19], v[236:239], v[200:203], v[16:19]
	v_mfma_f32_16x16x32_bf16 v[4:7], v[216:219], v[208:211], v[4:7]
	v_mfma_f32_16x16x32_bf16 v[0:3], v[236:239], v[208:211], v[0:3]
	s_add_i32 s21, 0, 0x18000
	v_add_u32_e32 v124, s21, v175
	s_barrier
	ds_read_b128 v[112:115], v124
	ds_read_b128 v[116:119], v124 offset:1024
	ds_read_b128 v[120:123], v124 offset:2048
	ds_read_b128 v[124:127], v124 offset:3072
	s_add_u32 s50, s50, 0x100000
	s_addc_u32 s51, s51, 0
	s_mov_b32 m0, s57
	v_lshl_add_u64 v[212:213], s[50:51], 0, v[156:157]
	ds_read_b128 v[132:135], v199 offset:32768
	ds_read_b128 v[136:139], v199 offset:33792
	ds_read_b128 v[162:165], v199 offset:34816
	ds_read_b128 v[166:169], v199 offset:35840
	ds_read_b128 v[170:173], v199 offset:36864
	ds_read_b128 v[200:203], v199 offset:37888
	ds_read_b128 v[204:207], v199 offset:38912
	ds_read_b128 v[208:211], v199 offset:39936
	global_load_lds_dwordx4 v[212:213], off
	v_lshl_add_u64 v[212:213], s[50:51], 0, v[154:155]
	s_mov_b32 m0, s58
	s_nop 0
	global_load_lds_dwordx4 v[212:213], off
	s_barrier
	s_waitcnt lgkmcnt(0)
	v_mfma_f32_16x16x32_bf16 v[148:151], v[112:115], v[132:135], v[148:151]
	v_mfma_f32_16x16x32_bf16 v[144:147], v[120:123], v[132:135], v[144:147]
	v_mfma_f32_16x16x32_bf16 v[108:111], v[112:115], v[162:165], v[108:111]
	v_mfma_f32_16x16x32_bf16 v[104:107], v[120:123], v[162:165], v[104:107]
	v_mfma_f32_16x16x32_bf16 v[92:95], v[112:115], v[170:173], v[92:95]
	v_mfma_f32_16x16x32_bf16 v[88:91], v[120:123], v[170:173], v[88:91]
	v_mfma_f32_16x16x32_bf16 v[76:79], v[112:115], v[204:207], v[76:79]
	v_mfma_f32_16x16x32_bf16 v[72:75], v[120:123], v[204:207], v[72:75]
	v_mfma_f32_16x16x32_bf16 v[148:151], v[116:119], v[136:139], v[148:151]
	v_mfma_f32_16x16x32_bf16 v[144:147], v[124:127], v[136:139], v[144:147]
	v_mfma_f32_16x16x32_bf16 v[108:111], v[116:119], v[166:169], v[108:111]
	v_mfma_f32_16x16x32_bf16 v[104:107], v[124:127], v[166:169], v[104:107]
	v_mfma_f32_16x16x32_bf16 v[92:95], v[116:119], v[200:203], v[92:95]
	v_mfma_f32_16x16x32_bf16 v[88:91], v[124:127], v[200:203], v[88:91]
	v_mfma_f32_16x16x32_bf16 v[76:79], v[116:119], v[208:211], v[76:79]
	v_mfma_f32_16x16x32_bf16 v[72:75], v[124:127], v[208:211], v[72:75]
	s_barrier
	s_add_i32 s50, 0, 0x1c000
	s_add_i32 s21, s21, s54
	v_add_u32_e32 v231, s50, v175
	v_lshl_add_u64 v[184:185], v[184:185], 0, s[52:53]
	s_mov_b32 m0, s21
	ds_read_b128 v[212:215], v231
	ds_read_b128 v[216:219], v231 offset:1024
	ds_read_b128 v[232:235], v231 offset:2048
	ds_read_b128 v[236:239], v231 offset:3072
	global_load_lds_dwordx4 v[184:185], off
	v_lshl_add_u64 v[184:185], v[192:193], 0, s[52:53]
	s_add_i32 m0, s21, 0x2000
	s_nop 0
	global_load_lds_dwordx4 v[184:185], off
	s_barrier
	s_waitcnt lgkmcnt(0)
	v_mfma_f32_16x16x32_bf16 v[140:143], v[212:215], v[132:135], v[140:143]
	v_mfma_f32_16x16x32_bf16 v[128:131], v[232:235], v[132:135], v[128:131]
	v_mfma_f32_16x16x32_bf16 v[100:103], v[212:215], v[162:165], v[100:103]
	v_mfma_f32_16x16x32_bf16 v[96:99], v[232:235], v[162:165], v[96:99]
	v_mfma_f32_16x16x32_bf16 v[84:87], v[212:215], v[170:173], v[84:87]
	v_mfma_f32_16x16x32_bf16 v[80:83], v[232:235], v[170:173], v[80:83]
	v_mfma_f32_16x16x32_bf16 v[68:71], v[212:215], v[204:207], v[68:71]
	v_mfma_f32_16x16x32_bf16 v[64:67], v[232:235], v[204:207], v[64:67]
	v_mfma_f32_16x16x32_bf16 v[140:143], v[216:219], v[136:139], v[140:143]
	v_mfma_f32_16x16x32_bf16 v[136:139], v[236:239], v[136:139], v[128:131]
	v_mfma_f32_16x16x32_bf16 v[100:103], v[216:219], v[166:169], v[100:103]
	v_mfma_f32_16x16x32_bf16 v[96:99], v[236:239], v[166:169], v[96:99]
	v_mfma_f32_16x16x32_bf16 v[84:87], v[216:219], v[200:203], v[84:87]
	v_mfma_f32_16x16x32_bf16 v[80:83], v[236:239], v[200:203], v[80:83]
	v_mfma_f32_16x16x32_bf16 v[68:71], v[216:219], v[208:211], v[68:71]
	v_mfma_f32_16x16x32_bf16 v[64:67], v[236:239], v[208:211], v[64:67]
	s_mov_b32 m0, s7
	v_lshl_add_u64 v[184:185], v[194:195], 0, s[52:53]
	s_barrier
	ds_read_b128 v[128:131], v199 offset:49152
	ds_read_b128 v[132:135], v199 offset:50176
	ds_read_b128 v[162:165], v199 offset:51200
	ds_read_b128 v[166:169], v199 offset:52224
	ds_read_b128 v[170:173], v199 offset:53248
	ds_read_b128 v[200:203], v199 offset:54272
	ds_read_b128 v[204:207], v199 offset:55296
	ds_read_b128 v[208:211], v199 offset:56320
	global_load_lds_dwordx4 v[184:185], off
	v_lshl_add_u64 v[184:185], v[240:241], 0, s[52:53]
	s_mov_b32 m0, s15
	s_nop 0
	global_load_lds_dwordx4 v[184:185], off
	s_barrier
	s_waitcnt lgkmcnt(0)
	v_mfma_f32_16x16x32_bf16 v[60:63], v[112:115], v[128:131], v[60:63]
	v_mfma_f32_16x16x32_bf16 v[56:59], v[120:123], v[128:131], v[56:59]
	v_mfma_f32_16x16x32_bf16 v[44:47], v[112:115], v[162:165], v[44:47]
	v_mfma_f32_16x16x32_bf16 v[40:43], v[120:123], v[162:165], v[40:43]
	v_mfma_f32_16x16x32_bf16 v[28:31], v[112:115], v[170:173], v[28:31]
	v_mfma_f32_16x16x32_bf16 v[24:27], v[120:123], v[170:173], v[24:27]
	v_mfma_f32_16x16x32_bf16 v[12:15], v[112:115], v[204:207], v[12:15]
	v_mfma_f32_16x16x32_bf16 v[8:11], v[120:123], v[204:207], v[8:11]
	v_mfma_f32_16x16x32_bf16 v[60:63], v[116:119], v[132:135], v[60:63]
	v_mfma_f32_16x16x32_bf16 v[56:59], v[124:127], v[132:135], v[56:59]
	v_mfma_f32_16x16x32_bf16 v[44:47], v[116:119], v[166:169], v[44:47]
	v_mfma_f32_16x16x32_bf16 v[40:43], v[124:127], v[166:169], v[40:43]
	v_mfma_f32_16x16x32_bf16 v[28:31], v[116:119], v[200:203], v[28:31]
	v_mfma_f32_16x16x32_bf16 v[24:27], v[124:127], v[200:203], v[24:27]
	v_mfma_f32_16x16x32_bf16 v[12:15], v[116:119], v[208:211], v[12:15]
	v_mfma_f32_16x16x32_bf16 v[8:11], v[124:127], v[208:211], v[8:11]
	s_barrier
	s_add_u32 s28, s28, 0x100080
	s_addc_u32 s29, s29, 0
	s_add_i32 s21, s50, s54
	v_lshl_add_u64 v[112:113], s[28:29], 0, v[176:177]
	s_mov_b32 m0, s21
	s_nop 0
	global_load_lds_dwordx4 v[112:113], off
	v_lshl_add_u64 v[112:113], s[28:29], 0, v[152:153]
	s_add_i32 m0, s21, 0x2000
	s_nop 0
	global_load_lds_dwordx4 v[112:113], off
	s_waitcnt vmcnt(6)
	s_barrier
	v_mfma_f32_16x16x32_bf16 v[52:55], v[212:215], v[128:131], v[52:55]
	v_mfma_f32_16x16x32_bf16 v[48:51], v[232:235], v[128:131], v[48:51]
	v_mfma_f32_16x16x32_bf16 v[36:39], v[212:215], v[162:165], v[36:39]
	v_mfma_f32_16x16x32_bf16 v[32:35], v[232:235], v[162:165], v[32:35]
	v_mfma_f32_16x16x32_bf16 v[20:23], v[212:215], v[170:173], v[20:23]
	v_mfma_f32_16x16x32_bf16 v[16:19], v[232:235], v[170:173], v[16:19]
	v_mfma_f32_16x16x32_bf16 v[4:7], v[212:215], v[204:207], v[4:7]
	v_mfma_f32_16x16x32_bf16 v[0:3], v[232:235], v[204:207], v[0:3]
	v_mfma_f32_16x16x32_bf16 v[52:55], v[216:219], v[132:135], v[52:55]
	v_mfma_f32_16x16x32_bf16 v[48:51], v[236:239], v[132:135], v[48:51]
	v_mfma_f32_16x16x32_bf16 v[36:39], v[216:219], v[166:169], v[36:39]
	v_mfma_f32_16x16x32_bf16 v[32:35], v[236:239], v[166:169], v[32:35]
	v_mfma_f32_16x16x32_bf16 v[20:23], v[216:219], v[200:203], v[20:23]
	v_mfma_f32_16x16x32_bf16 v[16:19], v[236:239], v[200:203], v[16:19]
	v_mfma_f32_16x16x32_bf16 v[4:7], v[216:219], v[208:211], v[4:7]
	v_mfma_f32_16x16x32_bf16 v[0:3], v[236:239], v[208:211], v[0:3]
	s_add_i32 s20, s20, 2
	s_add_u32 s48, s48, 0x100
	s_addc_u32 s49, s49, 0
	s_add_u32 vcc_lo, vcc_lo, 0x100
	s_addc_u32 vcc_hi, vcc_hi, 0
	s_cmp_gt_u32 s20, 61
	s_barrier
	s_cbranch_scc0 .LBB0_100
	v_lshl_or_b32 v162, s34, 8, v198
	v_lshl_add_u32 v166, s2, 8, v174
	v_ashrrev_i32_e32 v163, 31, v162
	v_lshlrev_b64 v[184:185], 1, v[162:163]
	v_ashrrev_i32_e32 v167, 31, v166
	v_lshl_add_u64 v[164:165], s[68:69], 0, v[184:185]
	v_lshlrev_b64 v[192:193], 11, v[166:167]
	v_lshl_add_u64 v[112:113], v[164:165], 0, v[192:193]
	global_load_dwordx4 v[200:203], v[112:113], off
	global_load_dwordx4 v[204:207], v[112:113], off offset:256
	v_or_b32_e32 v172, 16, v166
	v_ashrrev_i32_e32 v173, 31, v172
	v_lshlrev_b64 v[112:113], 11, v[172:173]
	v_or_b32_e32 v170, 32, v166
	v_lshl_add_u64 v[112:113], v[164:165], 0, v[112:113]
	v_ashrrev_i32_e32 v171, 31, v170
	global_load_dwordx4 v[132:135], v[112:113], off
	global_load_dwordx4 v[128:131], v[112:113], off offset:256
	v_lshlrev_b64 v[112:113], 11, v[170:171]
	v_or_b32_e32 v168, 48, v166
	v_lshl_add_u64 v[112:113], v[164:165], 0, v[112:113]
	v_ashrrev_i32_e32 v169, 31, v168
	global_load_dwordx4 v[124:127], v[112:113], off
	global_load_dwordx4 v[120:123], v[112:113], off offset:256
	v_lshlrev_b64 v[112:113], 11, v[168:169]
	v_lshl_add_u64 v[112:113], v[164:165], 0, v[112:113]
	global_load_dwordx4 v[116:119], v[112:113], off
	s_nop 0
	global_load_dwordx4 v[112:115], v[112:113], off offset:256
	v_add_u32_e32 v214, 0x80, v166
	v_ashrrev_i32_e32 v215, 31, v214
	v_lshlrev_b64 v[214:215], 11, v[214:215]
	v_lshl_add_u64 v[214:215], v[164:165], 0, v[214:215]
	global_load_dwordx4 v[208:211], v[214:215], off
	s_nop 0
	global_load_dwordx4 v[212:215], v[214:215], off offset:256
	v_add_u32_e32 v234, 0x90, v166
	v_ashrrev_i32_e32 v235, 31, v234
	v_lshlrev_b64 v[234:235], 11, v[234:235]
	v_lshl_add_u64 v[234:235], v[164:165], 0, v[234:235]
	global_load_dwordx4 v[216:219], v[234:235], off
	s_nop 0
	global_load_dwordx4 v[232:235], v[234:235], off offset:256
	v_add_u32_e32 v242, 0xa0, v166
	v_ashrrev_i32_e32 v243, 31, v242
	v_lshlrev_b64 v[242:243], 11, v[242:243]
	v_lshl_add_u64 v[242:243], v[164:165], 0, v[242:243]
	global_load_dwordx4 v[236:239], v[242:243], off
	s_nop 0
	global_load_dwordx4 v[240:243], v[242:243], off offset:256
	v_add_u32_e32 v250, 0xb0, v166
	v_ashrrev_i32_e32 v251, 31, v250
	v_lshlrev_b64 v[250:251], 11, v[250:251]
	v_lshl_add_u64 v[250:251], v[164:165], 0, v[250:251]
	global_load_dwordx4 v[244:247], v[250:251], off
	s_nop 0
	global_load_dwordx4 v[248:251], v[250:251], off offset:256
	s_lshl_b32 s48, s34, 2
	s_ashr_i32 s49, s48, 31
	s_waitcnt vmcnt(8)
	v_lshlrev_b32_e32 v194, 16, v200
	v_add_f32_e32 v148, v148, v194
	v_and_b32_e32 v194, 0xffff0000, v200
	v_add_f32_e32 v149, v149, v194
	v_lshlrev_b32_e32 v194, 16, v201
	v_add_f32_e32 v150, v150, v194
	v_and_b32_e32 v194, 0xffff0000, v201
	v_add_f32_e32 v151, v151, v194
	v_lshlrev_b32_e32 v194, 16, v202
	v_add_f32_e32 v194, v144, v194
	v_and_b32_e32 v144, 0xffff0000, v202
	v_add_f32_e32 v195, v145, v144
	v_lshlrev_b32_e32 v144, 16, v203
	v_add_f32_e32 v200, v146, v144
	v_and_b32_e32 v144, 0xffff0000, v203
	v_add_f32_e32 v147, v147, v144
	v_mul_f32_e32 v144, v194, v194
	v_mul_f32_e32 v145, v195, v195
	v_fmac_f32_e32 v144, v148, v148
	v_fmac_f32_e32 v145, v149, v149
	v_add_f32_e32 v144, v144, v145
	v_mul_f32_e32 v145, v200, v200
	v_fmac_f32_e32 v145, v150, v150
	v_add_f32_e32 v144, v145, v144
	v_mul_f32_e32 v145, v147, v147
	v_fmac_f32_e32 v145, v151, v151
	v_add_f32_e32 v201, v145, v144
	v_cvt_pk_bf16_f32 v144, v148, v149
	v_lshl_add_u64 v[148:149], s[64:65], 0, v[192:193]
	v_lshl_add_u64 v[148:149], v[148:149], 0, v[184:185]
	v_cvt_pk_bf16_f32 v145, v150, v151
	v_cvt_pk_bf16_f32 v146, v194, v195
	v_cvt_pk_bf16_f32 v147, v200, v147
	global_store_dwordx4 v[148:149], v[144:147], off
	s_nop 1
	v_lshlrev_b32_e32 v144, 16, v204
	v_add_f32_e32 v140, v140, v144
	v_and_b32_e32 v144, 0xffff0000, v204
	v_add_f32_e32 v141, v141, v144
	v_lshlrev_b32_e32 v144, 16, v205
	v_add_f32_e32 v142, v142, v144
	v_and_b32_e32 v144, 0xffff0000, v205
	v_add_f32_e32 v143, v143, v144
	v_lshlrev_b32_e32 v144, 16, v206
	v_add_f32_e32 v144, v136, v144
	v_and_b32_e32 v136, 0xffff0000, v206
	v_add_f32_e32 v145, v137, v136
	v_lshlrev_b32_e32 v136, 16, v207
	v_add_f32_e32 v146, v138, v136
	v_and_b32_e32 v136, 0xffff0000, v207
	v_add_f32_e32 v139, v139, v136
	v_mul_f32_e32 v136, v144, v144
	v_fmac_f32_e32 v136, v140, v140
	v_mul_f32_e32 v137, v145, v145
	v_add_f32_e32 v136, v136, v201
	v_fmac_f32_e32 v137, v141, v141
	v_add_f32_e32 v136, v137, v136
	v_mul_f32_e32 v137, v146, v146
	v_fmac_f32_e32 v137, v142, v142
	v_add_f32_e32 v136, v137, v136
	v_mul_f32_e32 v137, v139, v139
	v_fmac_f32_e32 v137, v143, v143
	v_add_f32_e32 v147, v137, v136
	v_cvt_pk_bf16_f32 v136, v140, v141
	v_cvt_pk_bf16_f32 v137, v142, v143
	v_cvt_pk_bf16_f32 v138, v144, v145
	v_cvt_pk_bf16_f32 v139, v146, v139
	global_store_dwordx4 v[148:149], v[136:139], off offset:256
	s_nop 1
	v_and_b32_e32 v137, 64, v225
	v_xor_b32_e32 v136, 16, v225
	v_add_u32_e32 v137, 64, v137
	v_cmp_lt_i32_e32 vcc, v136, v137
	v_xor_b32_e32 v139, 32, v225
	s_nop 0
	v_cndmask_b32_e32 v136, v225, v136, vcc
	v_lshlrev_b32_e32 v136, 2, v136
	ds_bpermute_b32 v138, v136, v147
	v_cmp_lt_i32_e32 vcc, v139, v137
	s_waitcnt lgkmcnt(0)
	v_add_f32_e32 v138, v147, v138
	v_cndmask_b32_e32 v137, v225, v139, vcc
	v_lshlrev_b32_e32 v137, 2, v137
	ds_bpermute_b32 v139, v137, v138
	s_and_saveexec_b64 s[28:29], s[38:39]
	s_cbranch_execz .LBB0_103
	v_lshlrev_b64 v[140:141], 6, v[166:167]
	v_lshl_add_u64 v[140:141], s[62:63], 0, v[140:141]
	v_lshl_add_u64 v[140:141], s[48:49], 2, v[140:141]
	s_lshl_b32 s34, s9, 2
	v_lshl_add_u64 v[140:141], v[140:141], 0, s[34:35]
	s_waitcnt lgkmcnt(0)
	v_add_f32_e32 v138, v138, v139
	global_store_dword v[140:141], v138, off

.LBB0_147:
	s_add_u32 s21, s0, 0xfffc0080
	s_addc_u32 s28, s1, -1
	s_add_i32 s60, 0, 0x10000
	v_add_u32_e32 v140, s60, v205
	ds_read_b128 v[128:131], v140
	ds_read_b128 v[132:135], v140 offset:1024
	ds_read_b128 v[136:139], v140 offset:2048
	ds_read_b128 v[140:143], v140 offset:3072
	s_cmp_eq_u32 s20, 12
	s_cselect_b32 s49, s43, s28
	s_cselect_b32 s48, s24, s21
	s_cselect_b32 s29, s25, vcc_hi
	s_cselect_b32 s28, s41, vcc_lo
	v_lshl_add_u64 v[174:175], s[0:1], 0, v[150:151]
	s_add_i32 m0, s57, 0xc000
	ds_read_b128 v[154:157], v208
	ds_read_b128 v[158:161], v208 offset:1024
	ds_read_b128 v[162:165], v208 offset:2048
	ds_read_b128 v[166:169], v208 offset:3072
	ds_read_b128 v[170:173], v208 offset:4096
	ds_read_b128 v[198:201], v208 offset:5120
	ds_read_b128 v[210:213], v208 offset:6144
	ds_read_b128 v[214:217], v208 offset:7168
	global_load_lds_dwordx4 v[174:175], off
	v_lshl_add_u64 v[174:175], s[0:1], 0, v[152:153]
	s_add_i32 m0, s57, 0xe000
	s_nop 0
	global_load_lds_dwordx4 v[174:175], off
	s_barrier
	s_waitcnt lgkmcnt(0)
	v_mfma_f32_16x16x32_bf16 v[124:127], v[128:131], v[154:157], v[124:127]
	v_mfma_f32_16x16x32_bf16 v[120:123], v[136:139], v[154:157], v[120:123]
	v_mfma_f32_16x16x32_bf16 v[108:111], v[128:131], v[162:165], v[108:111]
	v_mfma_f32_16x16x32_bf16 v[104:107], v[136:139], v[162:165], v[104:107]
	v_mfma_f32_16x16x32_bf16 v[92:95], v[128:131], v[170:173], v[92:95]
	v_mfma_f32_16x16x32_bf16 v[88:91], v[136:139], v[170:173], v[88:91]
	v_mfma_f32_16x16x32_bf16 v[76:79], v[128:131], v[210:213], v[76:79]
	v_mfma_f32_16x16x32_bf16 v[72:75], v[136:139], v[210:213], v[72:75]
	v_mfma_f32_16x16x32_bf16 v[124:127], v[132:135], v[158:161], v[124:127]
	v_mfma_f32_16x16x32_bf16 v[120:123], v[140:143], v[158:161], v[120:123]
	v_mfma_f32_16x16x32_bf16 v[108:111], v[132:135], v[166:169], v[108:111]
	v_mfma_f32_16x16x32_bf16 v[104:107], v[140:143], v[166:169], v[104:107]
	v_mfma_f32_16x16x32_bf16 v[92:95], v[132:135], v[198:201], v[92:95]
	v_mfma_f32_16x16x32_bf16 v[88:91], v[140:143], v[198:201], v[88:91]
	v_mfma_f32_16x16x32_bf16 v[76:79], v[132:135], v[214:217], v[76:79]
	v_mfma_f32_16x16x32_bf16 v[72:75], v[140:143], v[214:217], v[72:75]
	s_barrier
	s_add_i32 s21, 0, 0x14000
	v_add_u32_e32 v174, s21, v205
	s_add_i32 s60, s60, s56
	ds_read_b128 v[232:235], v174
	ds_read_b128 v[236:239], v174 offset:1024
	ds_read_b128 v[240:243], v174 offset:2048
	ds_read_b128 v[244:247], v174 offset:3072
	v_lshl_add_u64 v[174:175], s[28:29], 0, v[176:177]
	s_mov_b32 m0, s60
	v_lshl_add_u64 v[184:185], s[28:29], 0, v[144:145]
	global_load_lds_dwordx4 v[174:175], off
	s_add_i32 m0, s60, 0x2000
	s_nop 0
	global_load_lds_dwordx4 v[184:185], off
	s_barrier
	s_waitcnt lgkmcnt(0)
	v_mfma_f32_16x16x32_bf16 v[116:119], v[232:235], v[154:157], v[116:119]
	v_mfma_f32_16x16x32_bf16 v[112:115], v[240:243], v[154:157], v[112:115]
	v_mfma_f32_16x16x32_bf16 v[100:103], v[232:235], v[162:165], v[100:103]
	v_mfma_f32_16x16x32_bf16 v[96:99], v[240:243], v[162:165], v[96:99]
	v_mfma_f32_16x16x32_bf16 v[84:87], v[232:235], v[170:173], v[84:87]
	v_mfma_f32_16x16x32_bf16 v[80:83], v[240:243], v[170:173], v[80:83]
	v_mfma_f32_16x16x32_bf16 v[68:71], v[232:235], v[210:213], v[68:71]
	v_mfma_f32_16x16x32_bf16 v[64:67], v[240:243], v[210:213], v[64:67]
	v_mfma_f32_16x16x32_bf16 v[116:119], v[236:239], v[158:161], v[116:119]
	v_mfma_f32_16x16x32_bf16 v[112:115], v[244:247], v[158:161], v[112:115]
	v_mfma_f32_16x16x32_bf16 v[100:103], v[236:239], v[166:169], v[100:103]
	v_mfma_f32_16x16x32_bf16 v[96:99], v[244:247], v[166:169], v[96:99]
	v_mfma_f32_16x16x32_bf16 v[84:87], v[236:239], v[198:201], v[84:87]
	v_mfma_f32_16x16x32_bf16 v[80:83], v[244:247], v[198:201], v[80:83]
	v_mfma_f32_16x16x32_bf16 v[68:71], v[236:239], v[214:217], v[68:71]
	v_mfma_f32_16x16x32_bf16 v[64:67], v[244:247], v[214:217], v[64:67]
	s_mov_b32 m0, s57
	v_lshl_add_u64 v[192:193], s[48:49], 0, v[148:149]
	s_barrier
	ds_read_b128 v[154:157], v208 offset:16384
	ds_read_b128 v[158:161], v208 offset:17408
	ds_read_b128 v[162:165], v208 offset:18432
	ds_read_b128 v[166:169], v208 offset:19456
	ds_read_b128 v[170:173], v208 offset:20480
	ds_read_b128 v[198:201], v208 offset:21504
	ds_read_b128 v[210:213], v208 offset:22528
	ds_read_b128 v[214:217], v208 offset:23552
	global_load_lds_dwordx4 v[192:193], off
	v_lshl_add_u64 v[194:195], s[48:49], 0, v[146:147]
	s_mov_b32 m0, s58
	s_nop 0
	global_load_lds_dwordx4 v[194:195], off
	s_barrier
	s_waitcnt lgkmcnt(0)
	v_mfma_f32_16x16x32_bf16 v[60:63], v[128:131], v[154:157], v[60:63]
	v_mfma_f32_16x16x32_bf16 v[56:59], v[136:139], v[154:157], v[56:59]
	v_mfma_f32_16x16x32_bf16 v[44:47], v[128:131], v[162:165], v[44:47]
	v_mfma_f32_16x16x32_bf16 v[40:43], v[136:139], v[162:165], v[40:43]
	v_mfma_f32_16x16x32_bf16 v[28:31], v[128:131], v[170:173], v[28:31]
	v_mfma_f32_16x16x32_bf16 v[24:27], v[136:139], v[170:173], v[24:27]
	v_mfma_f32_16x16x32_bf16 v[12:15], v[128:131], v[210:213], v[12:15]
	v_mfma_f32_16x16x32_bf16 v[8:11], v[136:139], v[210:213], v[8:11]
	v_mfma_f32_16x16x32_bf16 v[60:63], v[132:135], v[158:161], v[60:63]
	v_mfma_f32_16x16x32_bf16 v[56:59], v[140:143], v[158:161], v[56:59]
	v_mfma_f32_16x16x32_bf16 v[44:47], v[132:135], v[166:169], v[44:47]
	v_mfma_f32_16x16x32_bf16 v[40:43], v[140:143], v[166:169], v[40:43]
	v_mfma_f32_16x16x32_bf16 v[28:31], v[132:135], v[198:201], v[28:31]
	v_mfma_f32_16x16x32_bf16 v[24:27], v[140:143], v[198:201], v[24:27]
	v_mfma_f32_16x16x32_bf16 v[12:15], v[132:135], v[214:217], v[12:15]
	v_mfma_f32_16x16x32_bf16 v[8:11], v[140:143], v[214:217], v[8:11]
	s_barrier
	s_add_u32 s60, s28, 0x40000
	s_addc_u32 s61, s29, 0
	s_add_i32 s21, s21, s56
	v_lshl_add_u64 v[128:129], s[60:61], 0, v[176:177]
	s_mov_b32 m0, s21
	s_nop 0
	global_load_lds_dwordx4 v[128:129], off
	v_lshl_add_u64 v[128:129], s[60:61], 0, v[144:145]
	s_add_i32 m0, s21, 0x2000
	s_nop 0
	global_load_lds_dwordx4 v[128:129], off
	s_waitcnt vmcnt(6)
	s_barrier
	v_mfma_f32_16x16x32_bf16 v[52:55], v[232:235], v[154:157], v[52:55]
	v_mfma_f32_16x16x32_bf16 v[48:51], v[240:243], v[154:157], v[48:51]
	v_mfma_f32_16x16x32_bf16 v[36:39], v[232:235], v[162:165], v[36:39]
	v_mfma_f32_16x16x32_bf16 v[32:35], v[240:243], v[162:165], v[32:35]
	v_mfma_f32_16x16x32_bf16 v[20:23], v[232:235], v[170:173], v[20:23]
	v_mfma_f32_16x16x32_bf16 v[16:19], v[240:243], v[170:173], v[16:19]
	v_mfma_f32_16x16x32_bf16 v[4:7], v[232:235], v[210:213], v[4:7]
	v_mfma_f32_16x16x32_bf16 v[0:3], v[240:243], v[210:213], v[0:3]
	v_mfma_f32_16x16x32_bf16 v[52:55], v[236:239], v[158:161], v[52:55]
	v_mfma_f32_16x16x32_bf16 v[48:51], v[244:247], v[158:161], v[48:51]
	v_mfma_f32_16x16x32_bf16 v[36:39], v[236:239], v[166:169], v[36:39]
	v_mfma_f32_16x16x32_bf16 v[32:35], v[244:247], v[166:169], v[32:35]
	v_mfma_f32_16x16x32_bf16 v[20:23], v[236:239], v[198:201], v[20:23]
	v_mfma_f32_16x16x32_bf16 v[16:19], v[244:247], v[198:201], v[16:19]
	v_mfma_f32_16x16x32_bf16 v[4:7], v[236:239], v[214:217], v[4:7]
	v_mfma_f32_16x16x32_bf16 v[0:3], v[244:247], v[214:217], v[0:3]
	s_add_i32 s21, 0, 0x18000
	v_add_u32_e32 v140, s21, v205
	s_barrier
	ds_read_b128 v[128:131], v140
	ds_read_b128 v[132:135], v140 offset:1024
	ds_read_b128 v[136:139], v140 offset:2048
	ds_read_b128 v[140:143], v140 offset:3072
	s_add_u32 s48, s48, 0x40000
	s_addc_u32 s49, s49, 0
	s_mov_b32 m0, s7
	v_lshl_add_u64 v[202:203], s[48:49], 0, v[148:149]
	ds_read_b128 v[154:157], v208 offset:32768
	ds_read_b128 v[158:161], v208 offset:33792
	ds_read_b128 v[162:165], v208 offset:34816
	ds_read_b128 v[166:169], v208 offset:35840
	ds_read_b128 v[170:173], v208 offset:36864
	ds_read_b128 v[198:201], v208 offset:37888
	ds_read_b128 v[210:213], v208 offset:38912
	ds_read_b128 v[214:217], v208 offset:39936
	global_load_lds_dwordx4 v[202:203], off
	v_lshl_add_u64 v[202:203], s[48:49], 0, v[146:147]
	s_mov_b32 m0, s15
	s_nop 0
	global_load_lds_dwordx4 v[202:203], off
	s_barrier
	s_waitcnt lgkmcnt(0)
	v_mfma_f32_16x16x32_bf16 v[124:127], v[128:131], v[154:157], v[124:127]
	v_mfma_f32_16x16x32_bf16 v[120:123], v[136:139], v[154:157], v[120:123]
	v_mfma_f32_16x16x32_bf16 v[108:111], v[128:131], v[162:165], v[108:111]
	v_mfma_f32_16x16x32_bf16 v[104:107], v[136:139], v[162:165], v[104:107]
	v_mfma_f32_16x16x32_bf16 v[92:95], v[128:131], v[170:173], v[92:95]
	v_mfma_f32_16x16x32_bf16 v[88:91], v[136:139], v[170:173], v[88:91]
	v_mfma_f32_16x16x32_bf16 v[76:79], v[128:131], v[210:213], v[76:79]
	v_mfma_f32_16x16x32_bf16 v[72:75], v[136:139], v[210:213], v[72:75]
	v_mfma_f32_16x16x32_bf16 v[124:127], v[132:135], v[158:161], v[124:127]
	v_mfma_f32_16x16x32_bf16 v[120:123], v[140:143], v[158:161], v[120:123]
	v_mfma_f32_16x16x32_bf16 v[108:111], v[132:135], v[166:169], v[108:111]
	v_mfma_f32_16x16x32_bf16 v[104:107], v[140:143], v[166:169], v[104:107]
	v_mfma_f32_16x16x32_bf16 v[92:95], v[132:135], v[198:201], v[92:95]
	v_mfma_f32_16x16x32_bf16 v[88:91], v[140:143], v[198:201], v[88:91]
	v_mfma_f32_16x16x32_bf16 v[76:79], v[132:135], v[214:217], v[76:79]
	v_mfma_f32_16x16x32_bf16 v[72:75], v[140:143], v[214:217], v[72:75]
	s_barrier
	s_add_i32 s48, 0, 0x1c000
	s_add_i32 s21, s21, s56
	v_add_u32_e32 v202, s48, v205
	v_lshl_add_u64 v[174:175], v[174:175], 0, s[52:53]
	s_mov_b32 m0, s21
	ds_read_b128 v[232:235], v202
	ds_read_b128 v[236:239], v202 offset:1024
	ds_read_b128 v[240:243], v202 offset:2048
	ds_read_b128 v[244:247], v202 offset:3072
	global_load_lds_dwordx4 v[174:175], off
	v_lshl_add_u64 v[174:175], v[184:185], 0, s[52:53]
	s_add_i32 m0, s21, 0x2000
	s_nop 0
	global_load_lds_dwordx4 v[174:175], off
	s_barrier
	s_waitcnt lgkmcnt(0)
	v_mfma_f32_16x16x32_bf16 v[116:119], v[232:235], v[154:157], v[116:119]
	v_mfma_f32_16x16x32_bf16 v[112:115], v[240:243], v[154:157], v[112:115]
	v_mfma_f32_16x16x32_bf16 v[100:103], v[232:235], v[162:165], v[100:103]
	v_mfma_f32_16x16x32_bf16 v[96:99], v[240:243], v[162:165], v[96:99]
	v_mfma_f32_16x16x32_bf16 v[84:87], v[232:235], v[170:173], v[84:87]
	v_mfma_f32_16x16x32_bf16 v[80:83], v[240:243], v[170:173], v[80:83]
	v_mfma_f32_16x16x32_bf16 v[68:71], v[232:235], v[210:213], v[68:71]
	v_mfma_f32_16x16x32_bf16 v[64:67], v[240:243], v[210:213], v[64:67]
	v_mfma_f32_16x16x32_bf16 v[116:119], v[236:239], v[158:161], v[116:119]
	v_mfma_f32_16x16x32_bf16 v[112:115], v[244:247], v[158:161], v[112:115]
	v_mfma_f32_16x16x32_bf16 v[100:103], v[236:239], v[166:169], v[100:103]
	v_mfma_f32_16x16x32_bf16 v[96:99], v[244:247], v[166:169], v[96:99]
	v_mfma_f32_16x16x32_bf16 v[84:87], v[236:239], v[198:201], v[84:87]
	v_mfma_f32_16x16x32_bf16 v[80:83], v[244:247], v[198:201], v[80:83]
	v_mfma_f32_16x16x32_bf16 v[68:71], v[236:239], v[214:217], v[68:71]
	v_mfma_f32_16x16x32_bf16 v[64:67], v[244:247], v[214:217], v[64:67]
	s_mov_b32 m0, s3
	v_lshl_add_u64 v[174:175], v[192:193], 0, s[52:53]
	s_barrier
	ds_read_b128 v[154:157], v208 offset:49152
	ds_read_b128 v[158:161], v208 offset:50176
	ds_read_b128 v[162:165], v208 offset:51200
	ds_read_b128 v[166:169], v208 offset:52224
	ds_read_b128 v[170:173], v208 offset:53248
	ds_read_b128 v[198:201], v208 offset:54272
	ds_read_b128 v[210:213], v208 offset:55296
	ds_read_b128 v[214:217], v208 offset:56320
	global_load_lds_dwordx4 v[174:175], off
	v_lshl_add_u64 v[174:175], v[194:195], 0, s[52:53]
	s_mov_b32 m0, s6
	s_nop 0
	global_load_lds_dwordx4 v[174:175], off
	s_barrier
	s_waitcnt lgkmcnt(0)
	v_mfma_f32_16x16x32_bf16 v[60:63], v[128:131], v[154:157], v[60:63]
	v_mfma_f32_16x16x32_bf16 v[56:59], v[136:139], v[154:157], v[56:59]
	v_mfma_f32_16x16x32_bf16 v[44:47], v[128:131], v[162:165], v[44:47]
	v_mfma_f32_16x16x32_bf16 v[40:43], v[136:139], v[162:165], v[40:43]
	v_mfma_f32_16x16x32_bf16 v[28:31], v[128:131], v[170:173], v[28:31]
	v_mfma_f32_16x16x32_bf16 v[24:27], v[136:139], v[170:173], v[24:27]
	v_mfma_f32_16x16x32_bf16 v[12:15], v[128:131], v[210:213], v[12:15]
	v_mfma_f32_16x16x32_bf16 v[8:11], v[136:139], v[210:213], v[8:11]
	v_mfma_f32_16x16x32_bf16 v[60:63], v[132:135], v[158:161], v[60:63]
	v_mfma_f32_16x16x32_bf16 v[56:59], v[140:143], v[158:161], v[56:59]
	v_mfma_f32_16x16x32_bf16 v[44:47], v[132:135], v[166:169], v[44:47]
	v_mfma_f32_16x16x32_bf16 v[40:43], v[140:143], v[166:169], v[40:43]
	v_mfma_f32_16x16x32_bf16 v[28:31], v[132:135], v[198:201], v[28:31]
	v_mfma_f32_16x16x32_bf16 v[24:27], v[140:143], v[198:201], v[24:27]
	v_mfma_f32_16x16x32_bf16 v[12:15], v[132:135], v[214:217], v[12:15]
	v_mfma_f32_16x16x32_bf16 v[8:11], v[140:143], v[214:217], v[8:11]
	s_barrier
	s_add_u32 s28, s28, 0x40080
	s_addc_u32 s29, s29, 0
	s_add_i32 s21, s48, s56
	v_lshl_add_u64 v[128:129], s[28:29], 0, v[176:177]
	s_mov_b32 m0, s21
	s_nop 0
	global_load_lds_dwordx4 v[128:129], off
	v_lshl_add_u64 v[128:129], s[28:29], 0, v[144:145]
	s_add_i32 m0, s21, 0x2000
	s_nop 0
	global_load_lds_dwordx4 v[128:129], off
	s_waitcnt vmcnt(6)
	s_barrier
	v_mfma_f32_16x16x32_bf16 v[52:55], v[232:235], v[154:157], v[52:55]
	v_mfma_f32_16x16x32_bf16 v[48:51], v[240:243], v[154:157], v[48:51]
	v_mfma_f32_16x16x32_bf16 v[36:39], v[232:235], v[162:165], v[36:39]
	v_mfma_f32_16x16x32_bf16 v[32:35], v[240:243], v[162:165], v[32:35]
	v_mfma_f32_16x16x32_bf16 v[20:23], v[232:235], v[170:173], v[20:23]
	v_mfma_f32_16x16x32_bf16 v[16:19], v[240:243], v[170:173], v[16:19]
	v_mfma_f32_16x16x32_bf16 v[4:7], v[232:235], v[210:213], v[4:7]
	v_mfma_f32_16x16x32_bf16 v[0:3], v[240:243], v[210:213], v[0:3]
	v_mfma_f32_16x16x32_bf16 v[52:55], v[236:239], v[158:161], v[52:55]
	v_mfma_f32_16x16x32_bf16 v[48:51], v[244:247], v[158:161], v[48:51]
	v_mfma_f32_16x16x32_bf16 v[36:39], v[236:239], v[166:169], v[36:39]
	v_mfma_f32_16x16x32_bf16 v[32:35], v[244:247], v[166:169], v[32:35]
	v_mfma_f32_16x16x32_bf16 v[20:23], v[236:239], v[198:201], v[20:23]
	v_mfma_f32_16x16x32_bf16 v[16:19], v[244:247], v[198:201], v[16:19]
	v_mfma_f32_16x16x32_bf16 v[4:7], v[236:239], v[214:217], v[4:7]
	v_mfma_f32_16x16x32_bf16 v[0:3], v[244:247], v[214:217], v[0:3]
	s_add_i32 s20, s20, 2
	s_add_u32 s0, s0, 0x100
	s_addc_u32 s1, s1, 0
	s_add_u32 vcc_lo, vcc_lo, 0x100
	s_addc_u32 vcc_hi, vcc_hi, 0
	s_cmp_gt_u32 s20, 13
	s_barrier
	s_cbranch_scc0 .LBB0_147
	s_cmp_eq_u32 s2, s51
	s_cselect_b64 s[48:49], -1, 0
	s_cmp_eq_u32 s2, s50
	v_lshl_add_u32 v170, s2, 8, v204
	s_cselect_b64 s[0:1], -1, 0
	s_or_b64 s[20:21], s[48:49], s[0:1]
	v_or_b32_e32 v166, 16, v170
	v_or_b32_e32 v164, 32, v170
	v_or_b32_e32 v162, 48, v170
	v_add_u32_e32 v160, 0x80, v170
	v_add_u32_e32 v158, 0x90, v170
	v_add_u32_e32 v156, 0xa0, v170
	v_add_u32_e32 v154, 0xb0, v170
	s_mov_b64 s[0:1], -1
	s_and_b64 vcc, exec, s[20:21]
	v_ashrrev_i32_e32 v171, 31, v170
	v_ashrrev_i32_e32 v167, 31, v166
	v_ashrrev_i32_e32 v165, 31, v164
	v_ashrrev_i32_e32 v163, 31, v162
	v_ashrrev_i32_e32 v161, 31, v160
	v_ashrrev_i32_e32 v159, 31, v158
	v_ashrrev_i32_e32 v157, 31, v156
	v_ashrrev_i32_e32 v155, 31, v154
	s_cbranch_vccnz .LBB0_150
	v_readlane_b32 s20, v253, 31
	v_lshlrev_b64 v[128:129], 6, v[170:171]
	v_readlane_b32 s21, v253, 32
	s_mov_b32 s0, 0x3727c5ac
	v_mov_b64_e32 v[198:199], s[0:1]
	v_lshl_add_u64 v[140:141], s[20:21], 0, v[128:129]
	global_load_dwordx4 v[128:131], v[140:141], off offset:32
	global_load_dwordx4 v[132:135], v[140:141], off offset:48
	global_load_dwordx4 v[136:139], v[140:141], off
	s_nop 0
	global_load_dwordx4 v[140:143], v[140:141], off offset:16
	s_mov_b32 s2, 0x3a800000
	s_mov_b32 s24, 0x45800000
	s_waitcnt vmcnt(0)
	v_pk_add_f32 v[128:129], v[128:129], v[132:133]
	v_pk_add_f32 v[130:131], v[130:131], v[134:135]
	v_pk_add_f32 v[136:137], v[136:137], v[140:141]
	v_pk_add_f32 v[138:139], v[138:139], v[142:143]
	v_pk_add_f32 v[172:173], v[136:137], v[128:129]
	v_lshlrev_b64 v[128:129], 6, v[166:167]
	v_lshl_add_u64 v[140:141], s[20:21], 0, v[128:129]
	v_pk_add_f32 v[168:169], v[138:139], v[130:131]
	global_load_dwordx4 v[128:131], v[140:141], off offset:32
	global_load_dwordx4 v[132:135], v[140:141], off offset:48
	global_load_dwordx4 v[136:139], v[140:141], off
	s_nop 0
	global_load_dwordx4 v[140:143], v[140:141], off offset:16
	s_waitcnt vmcnt(0)
	v_pk_add_f32 v[128:129], v[128:129], v[132:133]
	v_pk_add_f32 v[130:131], v[130:131], v[134:135]
	v_pk_add_f32 v[136:137], v[136:137], v[140:141]
	v_pk_add_f32 v[138:139], v[138:139], v[142:143]
	v_pk_add_f32 v[128:129], v[136:137], v[128:129]
	v_pk_add_f32 v[130:131], v[138:139], v[130:131]
	v_mov_b32_e32 v132, v128
	v_mov_b32_e32 v133, v172
	v_mov_b32_e32 v172, v129
	v_pk_add_f32 v[128:129], v[132:133], v[172:173]
	v_mov_b32_e32 v132, v130
	v_mov_b32_e32 v133, v168
	v_pk_add_f32 v[128:129], v[132:133], v[128:129]
	v_mov_b32_e32 v168, v131
	v_pk_add_f32 v[128:129], v[168:169], v[128:129]
	s_nop 0
	v_pk_fma_f32 v[128:129], v[128:129], s[2:3], v[198:199] op_sel_hi:[1,0,0]
	s_nop 0
	v_mul_f32_e32 v130, 0x4b800000, v129
	v_cmp_gt_f32_e64 s[0:1], s23, v129
	v_cmp_gt_f32_e32 vcc, s23, v128
	s_nop 0
	v_cndmask_b32_e64 v129, v129, v130, s[0:1]
	v_mul_f32_e32 v130, 0x4b800000, v128
	v_cndmask_b32_e32 v128, v128, v130, vcc
	v_rsq_f32_e32 v129, v129
	v_rsq_f32_e32 v128, v128
	s_nop 0
	v_pk_mul_f32 v[130:131], v[128:129], s[24:25] op_sel_hi:[1,0]
	s_nop 0
	v_cndmask_b32_e32 v169, v128, v130, vcc
	v_cndmask_b32_e64 v168, v129, v131, s[0:1]
	v_lshlrev_b64 v[128:129], 6, v[164:165]
	v_lshl_add_u64 v[140:141], s[20:21], 0, v[128:129]
	global_load_dwordx4 v[128:131], v[140:141], off offset:32
	global_load_dwordx4 v[132:135], v[140:141], off offset:48
	global_load_dwordx4 v[136:139], v[140:141], off
	s_nop 0
	global_load_dwordx4 v[140:143], v[140:141], off offset:16
	s_waitcnt vmcnt(0)
	v_pk_add_f32 v[128:129], v[128:129], v[132:133]
	v_pk_add_f32 v[130:131], v[130:131], v[134:135]
	v_pk_add_f32 v[136:137], v[136:137], v[140:141]
	v_pk_add_f32 v[138:139], v[138:139], v[142:143]
	v_pk_add_f32 v[174:175], v[136:137], v[128:129]
	v_lshlrev_b64 v[128:129], 6, v[162:163]
	v_lshl_add_u64 v[140:141], s[20:21], 0, v[128:129]
	v_pk_add_f32 v[172:173], v[138:139], v[130:131]
	global_load_dwordx4 v[128:131], v[140:141], off offset:32
	global_load_dwordx4 v[132:135], v[140:141], off offset:48
	global_load_dwordx4 v[136:139], v[140:141], off
	s_nop 0
	global_load_dwordx4 v[140:143], v[140:141], off offset:16
	s_waitcnt vmcnt(0)
	v_pk_add_f32 v[128:129], v[128:129], v[132:133]
	v_pk_add_f32 v[130:131], v[130:131], v[134:135]
	v_pk_add_f32 v[136:137], v[136:137], v[140:141]
	v_pk_add_f32 v[138:139], v[138:139], v[142:143]
	v_pk_add_f32 v[128:129], v[136:137], v[128:129]
	v_pk_add_f32 v[130:131], v[138:139], v[130:131]
	v_mov_b32_e32 v132, v128
	v_mov_b32_e32 v133, v174
	v_mov_b32_e32 v174, v129
	v_pk_add_f32 v[128:129], v[132:133], v[174:175]
	v_mov_b32_e32 v132, v130
	v_mov_b32_e32 v133, v172
	v_pk_add_f32 v[128:129], v[132:133], v[128:129]
	v_mov_b32_e32 v172, v131
	v_pk_add_f32 v[128:129], v[172:173], v[128:129]
	s_nop 0
	v_pk_fma_f32 v[128:129], v[128:129], s[2:3], v[198:199] op_sel_hi:[1,0,0]
	s_nop 0
	v_mul_f32_e32 v130, 0x4b800000, v129
	v_cmp_gt_f32_e64 s[0:1], s23, v129
	v_cmp_gt_f32_e32 vcc, s23, v128
	s_nop 0
	v_cndmask_b32_e64 v129, v129, v130, s[0:1]
	v_mul_f32_e32 v130, 0x4b800000, v128
	v_cndmask_b32_e32 v128, v128, v130, vcc
	v_rsq_f32_e32 v129, v129
	v_rsq_f32_e32 v128, v128
	s_nop 0
	v_pk_mul_f32 v[130:131], v[128:129], s[24:25] op_sel_hi:[1,0]
	s_nop 0
	v_cndmask_b32_e32 v173, v128, v130, vcc
	v_cndmask_b32_e64 v172, v129, v131, s[0:1]
	v_lshlrev_b64 v[128:129], 6, v[160:161]
	v_lshl_add_u64 v[140:141], s[20:21], 0, v[128:129]
	global_load_dwordx4 v[128:131], v[140:141], off offset:32
	global_load_dwordx4 v[132:135], v[140:141], off offset:48
	global_load_dwordx4 v[136:139], v[140:141], off
	s_nop 0
	global_load_dwordx4 v[140:143], v[140:141], off offset:16
	s_waitcnt vmcnt(0)
	v_pk_add_f32 v[128:129], v[128:129], v[132:133]
	v_pk_add_f32 v[130:131], v[130:131], v[134:135]
	v_pk_add_f32 v[136:137], v[136:137], v[140:141]
	v_pk_add_f32 v[138:139], v[138:139], v[142:143]
	v_pk_add_f32 v[184:185], v[136:137], v[128:129]
	v_lshlrev_b64 v[128:129], 6, v[158:159]
	v_lshl_add_u64 v[140:141], s[20:21], 0, v[128:129]
	v_pk_add_f32 v[174:175], v[138:139], v[130:131]
	global_load_dwordx4 v[128:131], v[140:141], off offset:32
	global_load_dwordx4 v[132:135], v[140:141], off offset:48
	global_load_dwordx4 v[136:139], v[140:141], off
	s_nop 0
	global_load_dwordx4 v[140:143], v[140:141], off offset:16
	s_waitcnt vmcnt(0)
	v_pk_add_f32 v[128:129], v[128:129], v[132:133]
	v_pk_add_f32 v[130:131], v[130:131], v[134:135]
	v_pk_add_f32 v[136:137], v[136:137], v[140:141]
	v_pk_add_f32 v[138:139], v[138:139], v[142:143]
	v_pk_add_f32 v[128:129], v[136:137], v[128:129]
	v_pk_add_f32 v[130:131], v[138:139], v[130:131]
	v_mov_b32_e32 v132, v128
	v_mov_b32_e32 v133, v184
	v_mov_b32_e32 v184, v129
	v_pk_add_f32 v[128:129], v[132:133], v[184:185]
	v_mov_b32_e32 v132, v130
	v_mov_b32_e32 v133, v174
	v_pk_add_f32 v[128:129], v[132:133], v[128:129]
	v_mov_b32_e32 v174, v131
	v_pk_add_f32 v[128:129], v[174:175], v[128:129]
	s_nop 0
	v_pk_fma_f32 v[128:129], v[128:129], s[2:3], v[198:199] op_sel_hi:[1,0,0]
	s_nop 0
	v_mul_f32_e32 v130, 0x4b800000, v129
	v_cmp_gt_f32_e64 s[0:1], s23, v129
	v_cmp_gt_f32_e32 vcc, s23, v128
	s_nop 0
	v_cndmask_b32_e64 v129, v129, v130, s[0:1]
	v_mul_f32_e32 v130, 0x4b800000, v128
	v_cndmask_b32_e32 v128, v128, v130, vcc
	v_rsq_f32_e32 v129, v129
	v_rsq_f32_e32 v128, v128
	s_nop 0
	v_pk_mul_f32 v[130:131], v[128:129], s[24:25] op_sel_hi:[1,0]
	s_nop 0
	v_cndmask_b32_e32 v175, v128, v130, vcc
	v_cndmask_b32_e64 v174, v129, v131, s[0:1]
	v_lshlrev_b64 v[128:129], 6, v[156:157]
	v_lshl_add_u64 v[140:141], s[20:21], 0, v[128:129]
	global_load_dwordx4 v[128:131], v[140:141], off offset:32
	global_load_dwordx4 v[132:135], v[140:141], off offset:48
	global_load_dwordx4 v[136:139], v[140:141], off
	s_nop 0
	global_load_dwordx4 v[140:143], v[140:141], off offset:16
	s_waitcnt vmcnt(0)
	v_pk_add_f32 v[128:129], v[128:129], v[132:133]
	v_pk_add_f32 v[130:131], v[130:131], v[134:135]
	v_pk_add_f32 v[136:137], v[136:137], v[140:141]
	v_pk_add_f32 v[138:139], v[138:139], v[142:143]
	v_pk_add_f32 v[202:203], v[136:137], v[128:129]
	v_lshlrev_b64 v[128:129], 6, v[154:155]
	v_lshl_add_u64 v[140:141], s[20:21], 0, v[128:129]
	v_pk_add_f32 v[200:201], v[138:139], v[130:131]
	global_load_dwordx4 v[128:131], v[140:141], off offset:32
	global_load_dwordx4 v[132:135], v[140:141], off offset:48
	global_load_dwordx4 v[136:139], v[140:141], off
	s_nop 0
	global_load_dwordx4 v[140:143], v[140:141], off offset:16
	s_waitcnt vmcnt(0)
	v_pk_add_f32 v[128:129], v[128:129], v[132:133]
	v_pk_add_f32 v[130:131], v[130:131], v[134:135]
	v_pk_add_f32 v[136:137], v[136:137], v[140:141]
	v_pk_add_f32 v[138:139], v[138:139], v[142:143]
	v_pk_add_f32 v[128:129], v[136:137], v[128:129]
	v_pk_add_f32 v[130:131], v[138:139], v[130:131]
	v_mov_b32_e32 v132, v128
	v_mov_b32_e32 v133, v202
	v_mov_b32_e32 v202, v129
	v_pk_add_f32 v[128:129], v[132:133], v[202:203]
	v_mov_b32_e32 v132, v130
	v_mov_b32_e32 v133, v200
	v_pk_add_f32 v[128:129], v[132:133], v[128:129]
	v_mov_b32_e32 v200, v131
	v_pk_add_f32 v[128:129], v[200:201], v[128:129]
	s_nop 0
	v_pk_fma_f32 v[128:129], v[128:129], s[2:3], v[198:199] op_sel_hi:[1,0,0]
	s_nop 0
	v_mul_f32_e32 v130, 0x4b800000, v129
	v_cmp_gt_f32_e64 s[0:1], s23, v129
	v_cmp_gt_f32_e32 vcc, s23, v128
	s_nop 0
	v_cndmask_b32_e64 v129, v129, v130, s[0:1]
	v_rsq_f32_e32 v131, v129
	v_mul_f32_e32 v129, 0x4b800000, v128
	v_cndmask_b32_e32 v128, v128, v129, vcc
	v_rsq_f32_e32 v130, v128
	s_nop 0
	v_pk_mul_f32 v[132:133], v[130:131], s[24:25] op_sel_hi:[1,0]
	s_nop 0
	v_cndmask_b32_e32 v129, v130, v132, vcc
	v_cndmask_b32_e64 v128, v131, v133, s[0:1]
	s_mov_b64 s[0:1], 0

.LBB0_170:
	s_add_u32 s20, s48, 0xfffc0080
	s_addc_u32 s21, s49, -1
	s_add_i32 s60, 0, 0x10000
	v_add_u32_e32 v140, s60, v232
	ds_read_b128 v[128:131], v140
	ds_read_b128 v[132:135], v140 offset:1024
	ds_read_b128 v[136:139], v140 offset:2048
	ds_read_b128 v[140:143], v140 offset:3072
	s_cmp_eq_u32 s57, 12
	s_cselect_b32 s51, s43, s21
	s_cselect_b32 s50, s24, s20
	s_cselect_b32 s29, s1, vcc_hi
	s_cselect_b32 s28, s25, vcc_lo
	v_lshl_add_u64 v[184:185], s[48:49], 0, v[204:205]
	s_add_i32 m0, s55, 0xc000
	ds_read_b128 v[144:147], v234
	ds_read_b128 v[148:151], v234 offset:1024
	ds_read_b128 v[152:155], v234 offset:2048
	ds_read_b128 v[156:159], v234 offset:3072
	ds_read_b128 v[160:163], v234 offset:4096
	ds_read_b128 v[164:167], v234 offset:5120
	ds_read_b128 v[168:171], v234 offset:6144
	ds_read_b128 v[172:175], v234 offset:7168
	global_load_lds_dwordx4 v[184:185], off
	v_lshl_add_u64 v[184:185], s[48:49], 0, v[206:207]
	s_add_i32 m0, s55, 0xe000
	s_nop 0
	global_load_lds_dwordx4 v[184:185], off
	s_barrier
	s_waitcnt lgkmcnt(0)
	v_mfma_f32_16x16x32_bf16 v[124:127], v[128:131], v[144:147], v[124:127]
	v_mfma_f32_16x16x32_bf16 v[120:123], v[136:139], v[144:147], v[120:123]
	v_mfma_f32_16x16x32_bf16 v[108:111], v[128:131], v[152:155], v[108:111]
	v_mfma_f32_16x16x32_bf16 v[104:107], v[136:139], v[152:155], v[104:107]
	v_mfma_f32_16x16x32_bf16 v[92:95], v[128:131], v[160:163], v[92:95]
	v_mfma_f32_16x16x32_bf16 v[88:91], v[136:139], v[160:163], v[88:91]
	v_mfma_f32_16x16x32_bf16 v[76:79], v[128:131], v[168:171], v[76:79]
	v_mfma_f32_16x16x32_bf16 v[72:75], v[136:139], v[168:171], v[72:75]
	v_mfma_f32_16x16x32_bf16 v[124:127], v[132:135], v[148:151], v[124:127]
	v_mfma_f32_16x16x32_bf16 v[120:123], v[140:143], v[148:151], v[120:123]
	v_mfma_f32_16x16x32_bf16 v[108:111], v[132:135], v[156:159], v[108:111]
	v_mfma_f32_16x16x32_bf16 v[104:107], v[140:143], v[156:159], v[104:107]
	v_mfma_f32_16x16x32_bf16 v[92:95], v[132:135], v[164:167], v[92:95]
	v_mfma_f32_16x16x32_bf16 v[88:91], v[140:143], v[164:167], v[88:91]
	v_mfma_f32_16x16x32_bf16 v[76:79], v[132:135], v[172:175], v[76:79]
	v_mfma_f32_16x16x32_bf16 v[72:75], v[140:143], v[172:175], v[72:75]
	s_barrier
	s_add_i32 s61, 0, 0x14000
	v_add_u32_e32 v184, s61, v232
	s_add_i32 s20, s60, s54
	ds_read_b128 v[208:211], v184
	ds_read_b128 v[212:215], v184 offset:1024
	ds_read_b128 v[216:219], v184 offset:2048
	ds_read_b128 v[236:239], v184 offset:3072
	v_lshl_add_u64 v[184:185], s[28:29], 0, v[176:177]
	s_mov_b32 m0, s20
	v_lshl_add_u64 v[192:193], s[28:29], 0, v[198:199]
	global_load_lds_dwordx4 v[184:185], off
	s_add_i32 m0, s20, 0x2000
	s_nop 0
	global_load_lds_dwordx4 v[192:193], off
	s_barrier
	s_waitcnt lgkmcnt(0)
	v_mfma_f32_16x16x32_bf16 v[116:119], v[208:211], v[144:147], v[116:119]
	v_mfma_f32_16x16x32_bf16 v[112:115], v[216:219], v[144:147], v[112:115]
	v_mfma_f32_16x16x32_bf16 v[100:103], v[208:211], v[152:155], v[100:103]
	v_mfma_f32_16x16x32_bf16 v[96:99], v[216:219], v[152:155], v[96:99]
	v_mfma_f32_16x16x32_bf16 v[84:87], v[208:211], v[160:163], v[84:87]
	v_mfma_f32_16x16x32_bf16 v[80:83], v[216:219], v[160:163], v[80:83]
	v_mfma_f32_16x16x32_bf16 v[68:71], v[208:211], v[168:171], v[68:71]
	v_mfma_f32_16x16x32_bf16 v[64:67], v[216:219], v[168:171], v[64:67]
	v_mfma_f32_16x16x32_bf16 v[116:119], v[212:215], v[148:151], v[116:119]
	v_mfma_f32_16x16x32_bf16 v[112:115], v[236:239], v[148:151], v[112:115]
	v_mfma_f32_16x16x32_bf16 v[100:103], v[212:215], v[156:159], v[100:103]
	v_mfma_f32_16x16x32_bf16 v[96:99], v[236:239], v[156:159], v[96:99]
	v_mfma_f32_16x16x32_bf16 v[84:87], v[212:215], v[164:167], v[84:87]
	v_mfma_f32_16x16x32_bf16 v[80:83], v[236:239], v[164:167], v[80:83]
	v_mfma_f32_16x16x32_bf16 v[68:71], v[212:215], v[172:175], v[68:71]
	v_mfma_f32_16x16x32_bf16 v[64:67], v[236:239], v[172:175], v[64:67]
	s_mov_b32 m0, s55
	v_lshl_add_u64 v[194:195], s[50:51], 0, v[202:203]
	s_barrier
	ds_read_b128 v[144:147], v234 offset:16384
	ds_read_b128 v[148:151], v234 offset:17408
	ds_read_b128 v[152:155], v234 offset:18432
	ds_read_b128 v[156:159], v234 offset:19456
	ds_read_b128 v[160:163], v234 offset:20480
	ds_read_b128 v[164:167], v234 offset:21504
	ds_read_b128 v[168:171], v234 offset:22528
	ds_read_b128 v[172:175], v234 offset:23552
	global_load_lds_dwordx4 v[194:195], off
	v_lshl_add_u64 v[240:241], s[50:51], 0, v[200:201]
	s_mov_b32 m0, s56
	s_nop 0
	global_load_lds_dwordx4 v[240:241], off
	s_barrier
	s_waitcnt lgkmcnt(0)
	v_mfma_f32_16x16x32_bf16 v[60:63], v[128:131], v[144:147], v[60:63]
	v_mfma_f32_16x16x32_bf16 v[56:59], v[136:139], v[144:147], v[56:59]
	v_mfma_f32_16x16x32_bf16 v[44:47], v[128:131], v[152:155], v[44:47]
	v_mfma_f32_16x16x32_bf16 v[40:43], v[136:139], v[152:155], v[40:43]
	v_mfma_f32_16x16x32_bf16 v[28:31], v[128:131], v[160:163], v[28:31]
	v_mfma_f32_16x16x32_bf16 v[24:27], v[136:139], v[160:163], v[24:27]
	v_mfma_f32_16x16x32_bf16 v[12:15], v[128:131], v[168:171], v[12:15]
	v_mfma_f32_16x16x32_bf16 v[8:11], v[136:139], v[168:171], v[8:11]
	v_mfma_f32_16x16x32_bf16 v[60:63], v[132:135], v[148:151], v[60:63]
	v_mfma_f32_16x16x32_bf16 v[56:59], v[140:143], v[148:151], v[56:59]
	v_mfma_f32_16x16x32_bf16 v[44:47], v[132:135], v[156:159], v[44:47]
	v_mfma_f32_16x16x32_bf16 v[40:43], v[140:143], v[156:159], v[40:43]
	v_mfma_f32_16x16x32_bf16 v[28:31], v[132:135], v[164:167], v[28:31]
	v_mfma_f32_16x16x32_bf16 v[24:27], v[140:143], v[164:167], v[24:27]
	v_mfma_f32_16x16x32_bf16 v[12:15], v[132:135], v[172:175], v[12:15]
	v_mfma_f32_16x16x32_bf16 v[8:11], v[140:143], v[172:175], v[8:11]
	s_barrier
	s_add_u32 s20, s28, 0x40000
	s_addc_u32 s21, s29, 0
	s_add_i32 s60, s61, s54
	v_lshl_add_u64 v[128:129], s[20:21], 0, v[176:177]
	s_mov_b32 m0, s60
	s_nop 0
	global_load_lds_dwordx4 v[128:129], off
	v_lshl_add_u64 v[128:129], s[20:21], 0, v[198:199]
	s_add_i32 m0, s60, 0x2000
	s_nop 0
	global_load_lds_dwordx4 v[128:129], off
	s_waitcnt vmcnt(6)
	s_barrier
	v_mfma_f32_16x16x32_bf16 v[52:55], v[208:211], v[144:147], v[52:55]
	v_mfma_f32_16x16x32_bf16 v[48:51], v[216:219], v[144:147], v[48:51]
	v_mfma_f32_16x16x32_bf16 v[36:39], v[208:211], v[152:155], v[36:39]
	v_mfma_f32_16x16x32_bf16 v[32:35], v[216:219], v[152:155], v[32:35]
	v_mfma_f32_16x16x32_bf16 v[20:23], v[208:211], v[160:163], v[20:23]
	v_mfma_f32_16x16x32_bf16 v[16:19], v[216:219], v[160:163], v[16:19]
	v_mfma_f32_16x16x32_bf16 v[4:7], v[208:211], v[168:171], v[4:7]
	v_mfma_f32_16x16x32_bf16 v[0:3], v[216:219], v[168:171], v[0:3]
	v_mfma_f32_16x16x32_bf16 v[52:55], v[212:215], v[148:151], v[52:55]
	v_mfma_f32_16x16x32_bf16 v[48:51], v[236:239], v[148:151], v[48:51]
	v_mfma_f32_16x16x32_bf16 v[36:39], v[212:215], v[156:159], v[36:39]
	v_mfma_f32_16x16x32_bf16 v[32:35], v[236:239], v[156:159], v[32:35]
	v_mfma_f32_16x16x32_bf16 v[20:23], v[212:215], v[164:167], v[20:23]
	v_mfma_f32_16x16x32_bf16 v[16:19], v[236:239], v[164:167], v[16:19]
	v_mfma_f32_16x16x32_bf16 v[4:7], v[212:215], v[172:175], v[4:7]
	v_mfma_f32_16x16x32_bf16 v[0:3], v[236:239], v[172:175], v[0:3]
	s_add_i32 s60, 0, 0x18000
	v_add_u32_e32 v140, s60, v232
	s_barrier
	ds_read_b128 v[128:131], v140
	ds_read_b128 v[132:135], v140 offset:1024
	ds_read_b128 v[136:139], v140 offset:2048
	ds_read_b128 v[140:143], v140 offset:3072
	s_add_u32 s20, s50, 0x40000
	s_addc_u32 s21, s51, 0
	s_mov_b32 m0, s7
	v_lshl_add_u64 v[208:209], s[20:21], 0, v[202:203]
	ds_read_b128 v[144:147], v234 offset:32768
	ds_read_b128 v[148:151], v234 offset:33792
	ds_read_b128 v[152:155], v234 offset:34816
	ds_read_b128 v[156:159], v234 offset:35840
	ds_read_b128 v[160:163], v234 offset:36864
	ds_read_b128 v[164:167], v234 offset:37888
	ds_read_b128 v[168:171], v234 offset:38912
	ds_read_b128 v[172:175], v234 offset:39936
	global_load_lds_dwordx4 v[208:209], off
	v_lshl_add_u64 v[208:209], s[20:21], 0, v[200:201]
	s_mov_b32 m0, s15
	s_nop 0
	global_load_lds_dwordx4 v[208:209], off
	s_barrier
	s_waitcnt lgkmcnt(0)
	v_mfma_f32_16x16x32_bf16 v[124:127], v[128:131], v[144:147], v[124:127]
	v_mfma_f32_16x16x32_bf16 v[120:123], v[136:139], v[144:147], v[120:123]
	v_mfma_f32_16x16x32_bf16 v[108:111], v[128:131], v[152:155], v[108:111]
	v_mfma_f32_16x16x32_bf16 v[104:107], v[136:139], v[152:155], v[104:107]
	v_mfma_f32_16x16x32_bf16 v[92:95], v[128:131], v[160:163], v[92:95]
	v_mfma_f32_16x16x32_bf16 v[88:91], v[136:139], v[160:163], v[88:91]
	v_mfma_f32_16x16x32_bf16 v[76:79], v[128:131], v[168:171], v[76:79]
	v_mfma_f32_16x16x32_bf16 v[72:75], v[136:139], v[168:171], v[72:75]
	v_mfma_f32_16x16x32_bf16 v[124:127], v[132:135], v[148:151], v[124:127]
	v_mfma_f32_16x16x32_bf16 v[120:123], v[140:143], v[148:151], v[120:123]
	v_mfma_f32_16x16x32_bf16 v[108:111], v[132:135], v[156:159], v[108:111]
	v_mfma_f32_16x16x32_bf16 v[104:107], v[140:143], v[156:159], v[104:107]
	v_mfma_f32_16x16x32_bf16 v[92:95], v[132:135], v[164:167], v[92:95]
	v_mfma_f32_16x16x32_bf16 v[88:91], v[140:143], v[164:167], v[88:91]
	v_mfma_f32_16x16x32_bf16 v[76:79], v[132:135], v[172:175], v[76:79]
	v_mfma_f32_16x16x32_bf16 v[72:75], v[140:143], v[172:175], v[72:75]
	s_barrier
	s_add_i32 s50, 0, 0x1c000
	s_add_i32 s20, s60, s54
	v_add_u32_e32 v235, s50, v232
	v_lshl_add_u64 v[184:185], v[184:185], 0, s[52:53]
	s_mov_b32 m0, s20
	ds_read_b128 v[208:211], v235
	ds_read_b128 v[212:215], v235 offset:1024
	ds_read_b128 v[216:219], v235 offset:2048
	ds_read_b128 v[236:239], v235 offset:3072
	global_load_lds_dwordx4 v[184:185], off
	v_lshl_add_u64 v[184:185], v[192:193], 0, s[52:53]
	s_add_i32 m0, s20, 0x2000
	s_nop 0
	global_load_lds_dwordx4 v[184:185], off
	s_barrier
	s_waitcnt lgkmcnt(0)
	v_mfma_f32_16x16x32_bf16 v[116:119], v[208:211], v[144:147], v[116:119]
	v_mfma_f32_16x16x32_bf16 v[112:115], v[216:219], v[144:147], v[112:115]
	v_mfma_f32_16x16x32_bf16 v[100:103], v[208:211], v[152:155], v[100:103]
	v_mfma_f32_16x16x32_bf16 v[96:99], v[216:219], v[152:155], v[96:99]
	v_mfma_f32_16x16x32_bf16 v[84:87], v[208:211], v[160:163], v[84:87]
	v_mfma_f32_16x16x32_bf16 v[80:83], v[216:219], v[160:163], v[80:83]
	v_mfma_f32_16x16x32_bf16 v[68:71], v[208:211], v[168:171], v[68:71]
	v_mfma_f32_16x16x32_bf16 v[64:67], v[216:219], v[168:171], v[64:67]
	v_mfma_f32_16x16x32_bf16 v[116:119], v[212:215], v[148:151], v[116:119]
	v_mfma_f32_16x16x32_bf16 v[112:115], v[236:239], v[148:151], v[112:115]
	v_mfma_f32_16x16x32_bf16 v[100:103], v[212:215], v[156:159], v[100:103]
	v_mfma_f32_16x16x32_bf16 v[96:99], v[236:239], v[156:159], v[96:99]
	v_mfma_f32_16x16x32_bf16 v[84:87], v[212:215], v[164:167], v[84:87]
	v_mfma_f32_16x16x32_bf16 v[80:83], v[236:239], v[164:167], v[80:83]
	v_mfma_f32_16x16x32_bf16 v[68:71], v[212:215], v[172:175], v[68:71]
	v_mfma_f32_16x16x32_bf16 v[64:67], v[236:239], v[172:175], v[64:67]
	s_mov_b32 m0, s3
	v_lshl_add_u64 v[184:185], v[194:195], 0, s[52:53]
	s_barrier
	ds_read_b128 v[144:147], v234 offset:49152
	ds_read_b128 v[148:151], v234 offset:50176
	ds_read_b128 v[152:155], v234 offset:51200
	ds_read_b128 v[156:159], v234 offset:52224
	ds_read_b128 v[160:163], v234 offset:53248
	ds_read_b128 v[164:167], v234 offset:54272
	ds_read_b128 v[168:171], v234 offset:55296
	ds_read_b128 v[172:175], v234 offset:56320
	global_load_lds_dwordx4 v[184:185], off
	v_lshl_add_u64 v[184:185], v[240:241], 0, s[52:53]
	s_mov_b32 m0, s6
	s_nop 0
	global_load_lds_dwordx4 v[184:185], off
	s_barrier
	s_waitcnt lgkmcnt(0)
	v_mfma_f32_16x16x32_bf16 v[60:63], v[128:131], v[144:147], v[60:63]
	v_mfma_f32_16x16x32_bf16 v[56:59], v[136:139], v[144:147], v[56:59]
	v_mfma_f32_16x16x32_bf16 v[44:47], v[128:131], v[152:155], v[44:47]
	v_mfma_f32_16x16x32_bf16 v[40:43], v[136:139], v[152:155], v[40:43]
	v_mfma_f32_16x16x32_bf16 v[28:31], v[128:131], v[160:163], v[28:31]
	v_mfma_f32_16x16x32_bf16 v[24:27], v[136:139], v[160:163], v[24:27]
	v_mfma_f32_16x16x32_bf16 v[12:15], v[128:131], v[168:171], v[12:15]
	v_mfma_f32_16x16x32_bf16 v[8:11], v[136:139], v[168:171], v[8:11]
	v_mfma_f32_16x16x32_bf16 v[60:63], v[132:135], v[148:151], v[60:63]
	v_mfma_f32_16x16x32_bf16 v[56:59], v[140:143], v[148:151], v[56:59]
	v_mfma_f32_16x16x32_bf16 v[44:47], v[132:135], v[156:159], v[44:47]
	v_mfma_f32_16x16x32_bf16 v[40:43], v[140:143], v[156:159], v[40:43]
	v_mfma_f32_16x16x32_bf16 v[28:31], v[132:135], v[164:167], v[28:31]
	v_mfma_f32_16x16x32_bf16 v[24:27], v[140:143], v[164:167], v[24:27]
	v_mfma_f32_16x16x32_bf16 v[12:15], v[132:135], v[172:175], v[12:15]
	v_mfma_f32_16x16x32_bf16 v[8:11], v[140:143], v[172:175], v[8:11]
	s_barrier
	s_add_u32 s20, s28, 0x40080
	s_addc_u32 s21, s29, 0
	s_add_i32 s28, s50, s54
	v_lshl_add_u64 v[128:129], s[20:21], 0, v[176:177]
	s_mov_b32 m0, s28
	s_nop 0
	global_load_lds_dwordx4 v[128:129], off
	v_lshl_add_u64 v[128:129], s[20:21], 0, v[198:199]
	s_add_i32 m0, s28, 0x2000
	s_nop 0
	global_load_lds_dwordx4 v[128:129], off
	s_waitcnt vmcnt(6)
	s_barrier
	v_mfma_f32_16x16x32_bf16 v[52:55], v[208:211], v[144:147], v[52:55]
	v_mfma_f32_16x16x32_bf16 v[48:51], v[216:219], v[144:147], v[48:51]
	v_mfma_f32_16x16x32_bf16 v[36:39], v[208:211], v[152:155], v[36:39]
	v_mfma_f32_16x16x32_bf16 v[32:35], v[216:219], v[152:155], v[32:35]
	v_mfma_f32_16x16x32_bf16 v[20:23], v[208:211], v[160:163], v[20:23]
	v_mfma_f32_16x16x32_bf16 v[16:19], v[216:219], v[160:163], v[16:19]
	v_mfma_f32_16x16x32_bf16 v[4:7], v[208:211], v[168:171], v[4:7]
	v_mfma_f32_16x16x32_bf16 v[0:3], v[216:219], v[168:171], v[0:3]
	v_mfma_f32_16x16x32_bf16 v[52:55], v[212:215], v[148:151], v[52:55]
	v_mfma_f32_16x16x32_bf16 v[48:51], v[236:239], v[148:151], v[48:51]
	v_mfma_f32_16x16x32_bf16 v[36:39], v[212:215], v[156:159], v[36:39]
	v_mfma_f32_16x16x32_bf16 v[32:35], v[236:239], v[156:159], v[32:35]
	v_mfma_f32_16x16x32_bf16 v[20:23], v[212:215], v[164:167], v[20:23]
	v_mfma_f32_16x16x32_bf16 v[16:19], v[236:239], v[164:167], v[16:19]
	v_mfma_f32_16x16x32_bf16 v[4:7], v[212:215], v[172:175], v[4:7]
	v_mfma_f32_16x16x32_bf16 v[0:3], v[236:239], v[172:175], v[0:3]
	s_add_i32 s57, s57, 2
	s_add_u32 s48, s48, 0x100
	s_addc_u32 s49, s49, 0
	s_add_u32 vcc_lo, vcc_lo, 0x100
	s_addc_u32 vcc_hi, vcc_hi, 0
	s_cmp_gt_u32 s57, 13
	s_barrier
	s_cbranch_scc0 .LBB0_170
	v_lshl_add_u32 v210, s2, 8, v231
	v_lshl_or_b32 v208, s34, 8, v233
	v_readlane_b32 s60, v252, 10
	v_ashrrev_i32_e32 v209, 31, v208
	v_readlane_b32 s61, v252, 11
	v_ashrrev_i32_e32 v211, 31, v210
	v_lshlrev_b64 v[128:129], 12, v[210:211]
	v_lshl_add_u64 v[212:213], v[208:209], 2, s[60:61]
	v_lshl_add_u64 v[128:129], v[212:213], 0, v[128:129]
	global_load_dwordx4 v[236:239], v[128:129], off offset:16
	global_load_dwordx4 v[240:243], v[128:129], off
	global_load_dwordx4 v[244:247], v[128:129], off offset:528
	global_load_dwordx4 v[248:251], v[128:129], off offset:512
	v_or_b32_e32 v218, 16, v210
	v_ashrrev_i32_e32 v219, 31, v218
	v_lshlrev_b64 v[128:129], 12, v[218:219]
	v_or_b32_e32 v216, 32, v210
	v_lshl_add_u64 v[128:129], v[212:213], 0, v[128:129]
	v_ashrrev_i32_e32 v217, 31, v216
	global_load_dwordx4 v[168:171], v[128:129], off offset:16
	global_load_dwordx4 v[172:175], v[128:129], off
	global_load_dwordx4 v[160:163], v[128:129], off offset:528
	global_load_dwordx4 v[164:167], v[128:129], off offset:512
	v_lshlrev_b64 v[128:129], 12, v[216:217]
	v_or_b32_e32 v214, 48, v210
	v_lshl_add_u64 v[128:129], v[212:213], 0, v[128:129]
	v_ashrrev_i32_e32 v215, 31, v214
	global_load_dwordx4 v[152:155], v[128:129], off offset:16
	global_load_dwordx4 v[156:159], v[128:129], off
	global_load_dwordx4 v[136:139], v[128:129], off offset:528
	global_load_dwordx4 v[144:147], v[128:129], off offset:512
	v_lshlrev_b64 v[128:129], 12, v[214:215]
	v_lshl_add_u64 v[132:133], v[212:213], 0, v[128:129]
	global_load_dwordx4 v[140:143], v[132:133], off offset:16
	global_load_dwordx4 v[148:151], v[132:133], off
	global_load_dwordx4 v[128:131], v[132:133], off offset:528
	s_nop 0
	global_load_dwordx4 v[132:135], v[132:133], off offset:512
	v_readlane_b32 s68, v252, 18
	v_readlane_b32 s69, v252, 19
	v_readlane_b32 s68, v255, 14
	v_readlane_b32 s69, v255, 15
	s_lshl_b32 s48, s34, 2
	s_ashr_i32 s49, s48, 31
	v_readlane_b32 s62, v252, 12
	v_readlane_b32 s63, v252, 13
	v_readlane_b32 s64, v252, 14
	v_readlane_b32 s65, v252, 15
	v_readlane_b32 s66, v252, 16
	v_readlane_b32 s67, v252, 17
	v_readlane_b32 s70, v252, 20
	v_readlane_b32 s71, v252, 21
	v_readlane_b32 s72, v252, 22
	v_readlane_b32 s73, v252, 23
	v_readlane_b32 s74, v252, 24
	v_readlane_b32 s75, v252, 25
	s_waitcnt vmcnt(0)
	v_pk_add_f32 v[184:185], v[122:123], v[238:239]
	v_pk_add_f32 v[122:123], v[120:121], v[236:237]
	v_pk_add_f32 v[124:125], v[124:125], v[240:241]
	v_mul_f32_e32 v120, v122, v122
	v_mul_f32_e32 v121, v123, v123
	v_fmac_f32_e32 v120, v124, v124
	v_fmac_f32_e32 v121, v125, v125
	v_pk_add_f32 v[126:127], v[126:127], v[242:243]
	v_add_f32_e32 v120, v120, v121
	v_mul_f32_e32 v121, v184, v184
	v_fmac_f32_e32 v121, v126, v126
	v_add_f32_e32 v120, v121, v120
	v_mul_f32_e32 v121, v185, v185
	v_fmac_f32_e32 v121, v127, v127
	v_add_f32_e32 v192, v121, v120
	v_cvt_pk_bf16_f32 v120, v124, v125
	v_lshlrev_b64 v[124:125], 11, v[210:211]
	v_lshl_add_u64 v[124:125], s[68:69], 0, v[124:125]
	v_cvt_pk_bf16_f32 v121, v126, v127
	v_lshl_add_u64 v[124:125], v[208:209], 1, v[124:125]
	v_cvt_pk_bf16_f32 v122, v122, v123
	v_cvt_pk_bf16_f32 v123, v184, v185
	global_store_dwordx4 v[124:125], v[120:123], off
	v_pk_add_f32 v[116:117], v[116:117], v[248:249]
	v_pk_add_f32 v[118:119], v[118:119], v[250:251]
	v_pk_add_f32 v[120:121], v[114:115], v[246:247]
	v_pk_add_f32 v[114:115], v[112:113], v[244:245]
	s_nop 0
	v_mul_f32_e32 v112, v114, v114
	v_fmac_f32_e32 v112, v116, v116
	v_mul_f32_e32 v113, v115, v115
	v_add_f32_e32 v112, v112, v192
	v_fmac_f32_e32 v113, v117, v117
	v_add_f32_e32 v112, v113, v112
	v_mul_f32_e32 v113, v120, v120
	v_fmac_f32_e32 v113, v118, v118
	v_add_f32_e32 v112, v113, v112
	v_mul_f32_e32 v113, v121, v121
	v_fmac_f32_e32 v113, v119, v119
	v_add_f32_e32 v122, v113, v112
	v_cvt_pk_bf16_f32 v112, v116, v117
	v_cvt_pk_bf16_f32 v113, v118, v119
	v_cvt_pk_bf16_f32 v114, v114, v115
	v_cvt_pk_bf16_f32 v115, v120, v121
	global_store_dwordx4 v[124:125], v[112:115], off offset:256
	s_nop 1
	v_and_b32_e32 v113, 64, v225
	v_xor_b32_e32 v112, 16, v225
	v_add_u32_e32 v113, 64, v113
	v_cmp_lt_i32_e32 vcc, v112, v113
	v_xor_b32_e32 v114, 32, v225
	s_nop 0
	v_cndmask_b32_e32 v112, v225, v112, vcc
	v_lshlrev_b32_e32 v235, 2, v112
	ds_bpermute_b32 v112, v235, v122
	v_cmp_lt_i32_e32 vcc, v114, v113
	s_waitcnt lgkmcnt(0)
	v_add_f32_e32 v112, v122, v112
	v_cndmask_b32_e32 v113, v225, v114, vcc
	v_lshlrev_b32_e32 v236, 2, v113
	ds_bpermute_b32 v113, v236, v112
	s_and_saveexec_b64 s[28:29], s[38:39]
	s_cbranch_execz .LBB0_173
	v_readlane_b32 s20, v253, 31
	v_lshlrev_b64 v[114:115], 6, v[210:211]
	v_readlane_b32 s21, v253, 32
	s_lshl_b32 s34, s58, 2
	s_waitcnt lgkmcnt(0)
	v_add_f32_e32 v112, v112, v113
	v_lshl_add_u64 v[114:115], s[20:21], 0, v[114:115]
	v_lshl_add_u64 v[114:115], s[48:49], 2, v[114:115]
	v_lshl_add_u64 v[114:115], v[114:115], 0, s[34:35]
	global_store_dword v[114:115], v112, off

.LBB0_292:
	s_add_u32 s20, s46, 0xfffc0080
	s_addc_u32 s21, s47, -1
	s_add_i32 s60, 0, 0x10000
	v_add_u32_e32 v138, s60, v141
	ds_read_b128 v[144:147], v138
	ds_read_b128 v[148:151], v138 offset:1024
	ds_read_b128 v[152:155], v138 offset:2048
	ds_read_b128 v[156:159], v138 offset:3072
	s_cmp_eq_u32 vcc_lo, 12
	s_cselect_b32 s49, s41, s21
	s_cselect_b32 s48, s24, s20
	s_cselect_b32 s29, s1, s59
	s_cselect_b32 s28, s25, s58
	v_lshl_add_u64 v[138:139], s[46:47], 0, v[134:135]
	s_add_i32 m0, s7, 0xc000
	ds_read_b128 v[160:163], v143
	ds_read_b128 v[164:167], v143 offset:1024
	ds_read_b128 v[168:171], v143 offset:2048
	ds_read_b128 v[172:175], v143 offset:3072
	ds_read_b128 v[198:201], v143 offset:4096
	ds_read_b128 v[202:205], v143 offset:5120
	ds_read_b128 v[206:209], v143 offset:6144
	ds_read_b128 v[210:213], v143 offset:7168
	global_load_lds_dwordx4 v[138:139], off
	v_lshl_add_u64 v[138:139], s[46:47], 0, v[136:137]
	s_add_i32 m0, s7, 0xe000
	s_nop 0
	global_load_lds_dwordx4 v[138:139], off
	s_barrier
	s_waitcnt lgkmcnt(0)
	v_mfma_f32_16x16x32_bf16 v[124:127], v[144:147], v[160:163], v[124:127]
	v_mfma_f32_16x16x32_bf16 v[120:123], v[152:155], v[160:163], v[120:123]
	v_mfma_f32_16x16x32_bf16 v[116:119], v[144:147], v[168:171], v[116:119]
	v_mfma_f32_16x16x32_bf16 v[108:111], v[152:155], v[168:171], v[108:111]
	v_mfma_f32_16x16x32_bf16 v[100:103], v[144:147], v[198:201], v[100:103]
	v_mfma_f32_16x16x32_bf16 v[92:95], v[152:155], v[198:201], v[92:95]
	v_mfma_f32_16x16x32_bf16 v[80:83], v[144:147], v[206:209], v[80:83]
	v_mfma_f32_16x16x32_bf16 v[72:75], v[152:155], v[206:209], v[72:75]
	v_mfma_f32_16x16x32_bf16 v[124:127], v[148:151], v[164:167], v[124:127]
	v_mfma_f32_16x16x32_bf16 v[120:123], v[156:159], v[164:167], v[120:123]
	v_mfma_f32_16x16x32_bf16 v[116:119], v[148:151], v[172:175], v[116:119]
	v_mfma_f32_16x16x32_bf16 v[108:111], v[156:159], v[172:175], v[108:111]
	v_mfma_f32_16x16x32_bf16 v[100:103], v[148:151], v[202:205], v[100:103]
	v_mfma_f32_16x16x32_bf16 v[92:95], v[156:159], v[202:205], v[92:95]
	v_mfma_f32_16x16x32_bf16 v[80:83], v[148:151], v[210:213], v[80:83]
	v_mfma_f32_16x16x32_bf16 v[72:75], v[156:159], v[210:213], v[72:75]
	s_barrier
	s_add_i32 s61, 0, 0x14000
	v_add_u32_e32 v138, s61, v141
	s_add_i32 s20, s60, s6
	ds_read_b128 v[214:217], v138
	ds_read_b128 v[232:235], v138 offset:1024
	ds_read_b128 v[236:239], v138 offset:2048
	ds_read_b128 v[240:243], v138 offset:3072
	v_lshl_add_u64 v[138:139], s[28:29], 0, v[176:177]
	s_mov_b32 m0, s20
	v_lshl_add_u64 v[218:219], s[28:29], 0, v[128:129]
	global_load_lds_dwordx4 v[138:139], off
	s_add_i32 m0, s20, 0x2000
	s_nop 0
	global_load_lds_dwordx4 v[218:219], off
	s_barrier
	s_waitcnt lgkmcnt(0)
	v_mfma_f32_16x16x32_bf16 v[112:115], v[214:217], v[160:163], v[112:115]
	v_mfma_f32_16x16x32_bf16 v[104:107], v[236:239], v[160:163], v[104:107]
	v_mfma_f32_16x16x32_bf16 v[96:99], v[214:217], v[168:171], v[96:99]
	v_mfma_f32_16x16x32_bf16 v[88:91], v[236:239], v[168:171], v[88:91]
	v_mfma_f32_16x16x32_bf16 v[84:87], v[214:217], v[198:201], v[84:87]
	v_mfma_f32_16x16x32_bf16 v[76:79], v[236:239], v[198:201], v[76:79]
	v_mfma_f32_16x16x32_bf16 v[68:71], v[214:217], v[206:209], v[68:71]
	v_mfma_f32_16x16x32_bf16 v[64:67], v[236:239], v[206:209], v[64:67]
	v_mfma_f32_16x16x32_bf16 v[112:115], v[232:235], v[164:167], v[112:115]
	v_mfma_f32_16x16x32_bf16 v[104:107], v[240:243], v[164:167], v[104:107]
	v_mfma_f32_16x16x32_bf16 v[96:99], v[232:235], v[172:175], v[96:99]
	v_mfma_f32_16x16x32_bf16 v[88:91], v[240:243], v[172:175], v[88:91]
	v_mfma_f32_16x16x32_bf16 v[84:87], v[232:235], v[202:205], v[84:87]
	v_mfma_f32_16x16x32_bf16 v[76:79], v[240:243], v[202:205], v[76:79]
	v_mfma_f32_16x16x32_bf16 v[68:71], v[232:235], v[210:213], v[68:71]
	v_mfma_f32_16x16x32_bf16 v[64:67], v[240:243], v[210:213], v[64:67]
	s_mov_b32 m0, s7
	v_lshl_add_u64 v[244:245], s[48:49], 0, v[132:133]
	s_barrier
	ds_read_b128 v[160:163], v143 offset:16384
	ds_read_b128 v[164:167], v143 offset:17408
	ds_read_b128 v[168:171], v143 offset:18432
	ds_read_b128 v[172:175], v143 offset:19456
	ds_read_b128 v[198:201], v143 offset:20480
	ds_read_b128 v[202:205], v143 offset:21504
	ds_read_b128 v[206:209], v143 offset:22528
	ds_read_b128 v[210:213], v143 offset:23552
	global_load_lds_dwordx4 v[244:245], off
	v_lshl_add_u64 v[246:247], s[48:49], 0, v[130:131]
	s_mov_b32 m0, s9
	s_nop 0
	global_load_lds_dwordx4 v[246:247], off
	s_barrier
	s_waitcnt lgkmcnt(0)
	v_mfma_f32_16x16x32_bf16 v[60:63], v[144:147], v[160:163], v[60:63]
	v_mfma_f32_16x16x32_bf16 v[56:59], v[152:155], v[160:163], v[56:59]
	v_mfma_f32_16x16x32_bf16 v[52:55], v[144:147], v[168:171], v[52:55]
	v_mfma_f32_16x16x32_bf16 v[44:47], v[152:155], v[168:171], v[44:47]
	v_mfma_f32_16x16x32_bf16 v[36:39], v[144:147], v[198:201], v[36:39]
	v_mfma_f32_16x16x32_bf16 v[28:31], v[152:155], v[198:201], v[28:31]
	v_mfma_f32_16x16x32_bf16 v[20:23], v[144:147], v[206:209], v[20:23]
	v_mfma_f32_16x16x32_bf16 v[12:15], v[152:155], v[206:209], v[12:15]
	v_mfma_f32_16x16x32_bf16 v[60:63], v[148:151], v[164:167], v[60:63]
	v_mfma_f32_16x16x32_bf16 v[56:59], v[156:159], v[164:167], v[56:59]
	v_mfma_f32_16x16x32_bf16 v[52:55], v[148:151], v[172:175], v[52:55]
	v_mfma_f32_16x16x32_bf16 v[44:47], v[156:159], v[172:175], v[44:47]
	v_mfma_f32_16x16x32_bf16 v[36:39], v[148:151], v[202:205], v[36:39]
	v_mfma_f32_16x16x32_bf16 v[28:31], v[156:159], v[202:205], v[28:31]
	v_mfma_f32_16x16x32_bf16 v[20:23], v[148:151], v[210:213], v[20:23]
	v_mfma_f32_16x16x32_bf16 v[12:15], v[156:159], v[210:213], v[12:15]
	s_barrier
	s_add_u32 s20, s28, 0x40000
	s_addc_u32 s21, s29, 0
	s_add_i32 s60, s61, s6
	v_lshl_add_u64 v[144:145], s[20:21], 0, v[176:177]
	s_mov_b32 m0, s60
	s_nop 0
	global_load_lds_dwordx4 v[144:145], off
	v_lshl_add_u64 v[144:145], s[20:21], 0, v[128:129]
	s_add_i32 m0, s60, 0x2000
	s_nop 0
	global_load_lds_dwordx4 v[144:145], off
	s_waitcnt vmcnt(6)
	s_barrier
	v_mfma_f32_16x16x32_bf16 v[48:51], v[214:217], v[160:163], v[48:51]
	v_mfma_f32_16x16x32_bf16 v[40:43], v[236:239], v[160:163], v[40:43]
	v_mfma_f32_16x16x32_bf16 v[32:35], v[214:217], v[168:171], v[32:35]
	v_mfma_f32_16x16x32_bf16 v[24:27], v[236:239], v[168:171], v[24:27]
	v_mfma_f32_16x16x32_bf16 v[16:19], v[214:217], v[198:201], v[16:19]
	v_mfma_f32_16x16x32_bf16 v[8:11], v[236:239], v[198:201], v[8:11]
	v_mfma_f32_16x16x32_bf16 v[4:7], v[214:217], v[206:209], v[4:7]
	v_mfma_f32_16x16x32_bf16 v[0:3], v[236:239], v[206:209], v[0:3]
	v_mfma_f32_16x16x32_bf16 v[48:51], v[232:235], v[164:167], v[48:51]
	v_mfma_f32_16x16x32_bf16 v[40:43], v[240:243], v[164:167], v[40:43]
	v_mfma_f32_16x16x32_bf16 v[32:35], v[232:235], v[172:175], v[32:35]
	v_mfma_f32_16x16x32_bf16 v[24:27], v[240:243], v[172:175], v[24:27]
	v_mfma_f32_16x16x32_bf16 v[16:19], v[232:235], v[202:205], v[16:19]
	v_mfma_f32_16x16x32_bf16 v[8:11], v[240:243], v[202:205], v[8:11]
	v_mfma_f32_16x16x32_bf16 v[4:7], v[232:235], v[210:213], v[4:7]
	v_mfma_f32_16x16x32_bf16 v[0:3], v[240:243], v[210:213], v[0:3]
	s_add_i32 s60, 0, 0x18000
	v_add_u32_e32 v156, s60, v141
	s_barrier
	ds_read_b128 v[144:147], v156
	ds_read_b128 v[148:151], v156 offset:1024
	ds_read_b128 v[152:155], v156 offset:2048
	ds_read_b128 v[156:159], v156 offset:3072
	s_add_u32 s20, s48, 0x40000
	s_addc_u32 s21, s49, 0
	s_mov_b32 m0, s15
	v_lshl_add_u64 v[214:215], s[20:21], 0, v[132:133]
	ds_read_b128 v[160:163], v143 offset:32768
	ds_read_b128 v[164:167], v143 offset:33792
	ds_read_b128 v[168:171], v143 offset:34816
	ds_read_b128 v[172:175], v143 offset:35840
	ds_read_b128 v[198:201], v143 offset:36864
	ds_read_b128 v[202:205], v143 offset:37888
	ds_read_b128 v[206:209], v143 offset:38912
	ds_read_b128 v[210:213], v143 offset:39936
	global_load_lds_dwordx4 v[214:215], off
	v_lshl_add_u64 v[214:215], s[20:21], 0, v[130:131]
	s_mov_b32 m0, s34
	s_nop 0
	global_load_lds_dwordx4 v[214:215], off
	s_barrier
	s_waitcnt lgkmcnt(0)
	v_mfma_f32_16x16x32_bf16 v[124:127], v[144:147], v[160:163], v[124:127]
	v_mfma_f32_16x16x32_bf16 v[120:123], v[152:155], v[160:163], v[120:123]
	v_mfma_f32_16x16x32_bf16 v[116:119], v[144:147], v[168:171], v[116:119]
	v_mfma_f32_16x16x32_bf16 v[108:111], v[152:155], v[168:171], v[108:111]
	v_mfma_f32_16x16x32_bf16 v[100:103], v[144:147], v[198:201], v[100:103]
	v_mfma_f32_16x16x32_bf16 v[92:95], v[152:155], v[198:201], v[92:95]
	v_mfma_f32_16x16x32_bf16 v[80:83], v[144:147], v[206:209], v[80:83]
	v_mfma_f32_16x16x32_bf16 v[72:75], v[152:155], v[206:209], v[72:75]
	v_mfma_f32_16x16x32_bf16 v[124:127], v[148:151], v[164:167], v[124:127]
	v_mfma_f32_16x16x32_bf16 v[120:123], v[156:159], v[164:167], v[120:123]
	v_mfma_f32_16x16x32_bf16 v[116:119], v[148:151], v[172:175], v[116:119]
	v_mfma_f32_16x16x32_bf16 v[108:111], v[156:159], v[172:175], v[108:111]
	v_mfma_f32_16x16x32_bf16 v[100:103], v[148:151], v[202:205], v[100:103]
	v_mfma_f32_16x16x32_bf16 v[92:95], v[156:159], v[202:205], v[92:95]
	v_mfma_f32_16x16x32_bf16 v[80:83], v[148:151], v[210:213], v[80:83]
	v_mfma_f32_16x16x32_bf16 v[72:75], v[156:159], v[210:213], v[72:75]
	s_barrier
	s_add_i32 s48, 0, 0x1c000
	s_add_i32 s20, s60, s6
	v_add_u32_e32 v184, s48, v141
	v_lshl_add_u64 v[138:139], v[138:139], 0, s[52:53]
	s_mov_b32 m0, s20
	ds_read_b128 v[214:217], v184
	ds_read_b128 v[232:235], v184 offset:1024
	ds_read_b128 v[236:239], v184 offset:2048
	ds_read_b128 v[240:243], v184 offset:3072
	global_load_lds_dwordx4 v[138:139], off
	v_lshl_add_u64 v[138:139], v[218:219], 0, s[52:53]
	s_add_i32 m0, s20, 0x2000
	s_nop 0
	global_load_lds_dwordx4 v[138:139], off
	s_barrier
	s_waitcnt lgkmcnt(0)
	v_mfma_f32_16x16x32_bf16 v[112:115], v[214:217], v[160:163], v[112:115]
	v_mfma_f32_16x16x32_bf16 v[104:107], v[236:239], v[160:163], v[104:107]
	v_mfma_f32_16x16x32_bf16 v[96:99], v[214:217], v[168:171], v[96:99]
	v_mfma_f32_16x16x32_bf16 v[88:91], v[236:239], v[168:171], v[88:91]
	v_mfma_f32_16x16x32_bf16 v[84:87], v[214:217], v[198:201], v[84:87]
	v_mfma_f32_16x16x32_bf16 v[76:79], v[236:239], v[198:201], v[76:79]
	v_mfma_f32_16x16x32_bf16 v[68:71], v[214:217], v[206:209], v[68:71]
	v_mfma_f32_16x16x32_bf16 v[64:67], v[236:239], v[206:209], v[64:67]
	v_mfma_f32_16x16x32_bf16 v[112:115], v[232:235], v[164:167], v[112:115]
	v_mfma_f32_16x16x32_bf16 v[104:107], v[240:243], v[164:167], v[104:107]
	v_mfma_f32_16x16x32_bf16 v[96:99], v[232:235], v[172:175], v[96:99]
	v_mfma_f32_16x16x32_bf16 v[88:91], v[240:243], v[172:175], v[88:91]
	v_mfma_f32_16x16x32_bf16 v[84:87], v[232:235], v[202:205], v[84:87]
	v_mfma_f32_16x16x32_bf16 v[76:79], v[240:243], v[202:205], v[76:79]
	v_mfma_f32_16x16x32_bf16 v[68:71], v[232:235], v[210:213], v[68:71]
	v_mfma_f32_16x16x32_bf16 v[64:67], v[240:243], v[210:213], v[64:67]
	s_mov_b32 m0, s51
	v_lshl_add_u64 v[138:139], v[244:245], 0, s[52:53]
	s_barrier
	ds_read_b128 v[160:163], v143 offset:49152
	ds_read_b128 v[164:167], v143 offset:50176
	ds_read_b128 v[168:171], v143 offset:51200
	ds_read_b128 v[172:175], v143 offset:52224
	ds_read_b128 v[198:201], v143 offset:53248
	ds_read_b128 v[202:205], v143 offset:54272
	ds_read_b128 v[206:209], v143 offset:55296
	ds_read_b128 v[210:213], v143 offset:56320
	global_load_lds_dwordx4 v[138:139], off
	v_lshl_add_u64 v[138:139], v[246:247], 0, s[52:53]
	s_mov_b32 m0, s54
	s_nop 0
	global_load_lds_dwordx4 v[138:139], off
	s_barrier
	s_waitcnt lgkmcnt(0)
	v_mfma_f32_16x16x32_bf16 v[60:63], v[144:147], v[160:163], v[60:63]
	v_mfma_f32_16x16x32_bf16 v[56:59], v[152:155], v[160:163], v[56:59]
	v_mfma_f32_16x16x32_bf16 v[52:55], v[144:147], v[168:171], v[52:55]
	v_mfma_f32_16x16x32_bf16 v[44:47], v[152:155], v[168:171], v[44:47]
	v_mfma_f32_16x16x32_bf16 v[36:39], v[144:147], v[198:201], v[36:39]
	v_mfma_f32_16x16x32_bf16 v[28:31], v[152:155], v[198:201], v[28:31]
	v_mfma_f32_16x16x32_bf16 v[20:23], v[144:147], v[206:209], v[20:23]
	v_mfma_f32_16x16x32_bf16 v[12:15], v[152:155], v[206:209], v[12:15]
	v_mfma_f32_16x16x32_bf16 v[60:63], v[148:151], v[164:167], v[60:63]
	v_mfma_f32_16x16x32_bf16 v[56:59], v[156:159], v[164:167], v[56:59]
	v_mfma_f32_16x16x32_bf16 v[52:55], v[148:151], v[172:175], v[52:55]
	v_mfma_f32_16x16x32_bf16 v[44:47], v[156:159], v[172:175], v[44:47]
	v_mfma_f32_16x16x32_bf16 v[36:39], v[148:151], v[202:205], v[36:39]
	v_mfma_f32_16x16x32_bf16 v[28:31], v[156:159], v[202:205], v[28:31]
	v_mfma_f32_16x16x32_bf16 v[20:23], v[148:151], v[210:213], v[20:23]
	v_mfma_f32_16x16x32_bf16 v[12:15], v[156:159], v[210:213], v[12:15]
	s_barrier
	s_add_u32 s20, s28, 0x40080
	s_addc_u32 s21, s29, 0
	s_add_i32 s28, s48, s6
	v_lshl_add_u64 v[138:139], s[20:21], 0, v[176:177]
	s_mov_b32 m0, s28
	s_nop 0
	global_load_lds_dwordx4 v[138:139], off
	v_lshl_add_u64 v[138:139], s[20:21], 0, v[128:129]
	s_add_i32 m0, s28, 0x2000
	s_nop 0
	global_load_lds_dwordx4 v[138:139], off
	s_waitcnt vmcnt(6)
	s_barrier
	v_mfma_f32_16x16x32_bf16 v[48:51], v[214:217], v[160:163], v[48:51]
	v_mfma_f32_16x16x32_bf16 v[40:43], v[236:239], v[160:163], v[40:43]
	v_mfma_f32_16x16x32_bf16 v[32:35], v[214:217], v[168:171], v[32:35]
	v_mfma_f32_16x16x32_bf16 v[24:27], v[236:239], v[168:171], v[24:27]
	v_mfma_f32_16x16x32_bf16 v[16:19], v[214:217], v[198:201], v[16:19]
	v_mfma_f32_16x16x32_bf16 v[8:11], v[236:239], v[198:201], v[8:11]
	v_mfma_f32_16x16x32_bf16 v[4:7], v[214:217], v[206:209], v[4:7]
	v_mfma_f32_16x16x32_bf16 v[0:3], v[236:239], v[206:209], v[0:3]
	v_mfma_f32_16x16x32_bf16 v[48:51], v[232:235], v[164:167], v[48:51]
	v_mfma_f32_16x16x32_bf16 v[40:43], v[240:243], v[164:167], v[40:43]
	v_mfma_f32_16x16x32_bf16 v[32:35], v[232:235], v[172:175], v[32:35]
	v_mfma_f32_16x16x32_bf16 v[24:27], v[240:243], v[172:175], v[24:27]
	v_mfma_f32_16x16x32_bf16 v[16:19], v[232:235], v[202:205], v[16:19]
	v_mfma_f32_16x16x32_bf16 v[8:11], v[240:243], v[202:205], v[8:11]
	v_mfma_f32_16x16x32_bf16 v[4:7], v[232:235], v[210:213], v[4:7]
	v_mfma_f32_16x16x32_bf16 v[0:3], v[240:243], v[210:213], v[0:3]
	s_add_i32 vcc_lo, vcc_lo, 2
	s_add_u32 s46, s46, 0x100
	s_addc_u32 s47, s47, 0
	s_add_u32 s58, s58, 0x100
	s_addc_u32 s59, s59, 0
	s_cmp_gt_u32 vcc_lo, 13
	s_barrier
	s_cbranch_scc0 .LBB0_292
	v_lshl_add_u32 v144, s57, 8, v140
	v_lshl_or_b32 v138, s2, 8, v142
	v_ashrrev_i32_e32 v145, 31, v144
	v_readlane_b32 s20, v254, 43
	v_ashrrev_i32_e32 v139, 31, v138
	v_lshlrev_b64 v[146:147], 16, v[144:145]
	v_readlane_b32 s21, v254, 44
	v_lshlrev_b64 v[148:149], 1, v[138:139]
	v_cvt_pk_bf16_f32 v124, v124, v125
	v_cvt_pk_bf16_f32 v125, v126, v127
	v_cvt_pk_bf16_f32 v126, v120, v121
	v_cvt_pk_bf16_f32 v127, v122, v123
	s_nop 0
	v_lshl_add_u64 v[146:147], s[20:21], 0, v[146:147]
	v_lshl_add_u64 v[138:139], v[146:147], 0, v[148:149]
	global_store_dwordx4 v[138:139], v[124:127], off
	v_cvt_pk_bf16_f32 v112, v112, v113
	v_cvt_pk_bf16_f32 v113, v114, v115
	v_cvt_pk_bf16_f32 v114, v104, v105
	v_or_b32_e32 v104, 16, v144
	v_ashrrev_i32_e32 v105, 31, v104
	v_lshlrev_b64 v[104:105], 16, v[104:105]
	v_lshl_add_u64 v[104:105], s[20:21], 0, v[104:105]
	v_cvt_pk_bf16_f32 v115, v106, v107
	global_store_dwordx4 v[138:139], v[112:115], off offset:256
	s_mov_b32 s1, 0x900000
	s_mov_b32 s2, s0
	v_lshl_add_u64 v[112:113], v[104:105], 0, v[148:149]
	v_cvt_pk_bf16_f32 v104, v116, v117
	v_cvt_pk_bf16_f32 v105, v118, v119
	v_cvt_pk_bf16_f32 v106, v108, v109
	v_cvt_pk_bf16_f32 v107, v110, v111
	global_store_dwordx4 v[112:113], v[104:107], off
	v_cvt_pk_bf16_f32 v96, v96, v97
	v_cvt_pk_bf16_f32 v97, v98, v99
	v_cvt_pk_bf16_f32 v98, v88, v89
	v_or_b32_e32 v88, 32, v144
	v_ashrrev_i32_e32 v89, 31, v88
	v_lshlrev_b64 v[88:89], 16, v[88:89]
	v_lshl_add_u64 v[88:89], s[20:21], 0, v[88:89]
	v_cvt_pk_bf16_f32 v99, v90, v91
	global_store_dwordx4 v[112:113], v[96:99], off offset:256
	s_mov_b32 s57, s40
	s_mov_b64 s[28:29], s[44:45]
	v_lshl_add_u64 v[96:97], v[88:89], 0, v[148:149]
	v_cvt_pk_bf16_f32 v88, v100, v101
	v_cvt_pk_bf16_f32 v89, v102, v103
	v_cvt_pk_bf16_f32 v90, v92, v93
	v_cvt_pk_bf16_f32 v91, v94, v95
	global_store_dwordx4 v[96:97], v[88:91], off
	v_cvt_pk_bf16_f32 v84, v84, v85
	v_cvt_pk_bf16_f32 v85, v86, v87
	v_cvt_pk_bf16_f32 v86, v76, v77
	v_or_b32_e32 v76, 48, v144
	v_ashrrev_i32_e32 v77, 31, v76
	v_lshlrev_b64 v[76:77], 16, v[76:77]
	v_lshl_add_u64 v[76:77], s[20:21], 0, v[76:77]
	v_cvt_pk_bf16_f32 v87, v78, v79
	global_store_dwordx4 v[96:97], v[84:87], off offset:256
	s_mov_b64 s[20:21], 0x800000
	s_mov_b64 s[46:47], s[42:43]
	v_lshl_add_u64 v[84:85], v[76:77], 0, v[148:149]
	v_cvt_pk_bf16_f32 v76, v80, v81
	v_cvt_pk_bf16_f32 v77, v82, v83
	v_cvt_pk_bf16_f32 v78, v72, v73
	v_cvt_pk_bf16_f32 v79, v74, v75
	global_store_dwordx4 v[84:85], v[76:79], off
	v_cvt_pk_bf16_f32 v68, v68, v69
	v_cvt_pk_bf16_f32 v69, v70, v71
	v_cvt_pk_bf16_f32 v70, v64, v65
	v_cvt_pk_bf16_f32 v71, v66, v67
	global_store_dwordx4 v[84:85], v[68:71], off offset:256
	v_cvt_pk_bf16_f32 v60, v60, v61
	v_cvt_pk_bf16_f32 v61, v62, v63
	v_cvt_pk_bf16_f32 v62, v56, v57
	v_add_co_u32_e32 v56, vcc, s23, v138
	v_lshl_add_u64 v[64:65], v[138:139], 0, s[20:21]
	s_nop 0
	v_addc_co_u32_e32 v57, vcc, 0, v139, vcc
	v_cvt_pk_bf16_f32 v63, v58, v59
	global_store_dwordx4 v[56:57], v[60:63], off
	v_cvt_pk_bf16_f32 v48, v48, v49
	v_cvt_pk_bf16_f32 v49, v50, v51
	v_cvt_pk_bf16_f32 v50, v40, v41
	v_cvt_pk_bf16_f32 v51, v42, v43
	global_store_dwordx4 v[64:65], v[48:51], off offset:256
	s_mov_b64 s[20:21], 0x900000
	v_cvt_pk_bf16_f32 v40, v52, v53
	v_cvt_pk_bf16_f32 v41, v54, v55
	v_cvt_pk_bf16_f32 v42, v44, v45
	v_add_co_u32_e32 v44, vcc, s1, v138
	v_lshl_add_u64 v[48:49], v[138:139], 0, s[20:21]
	s_nop 0
	v_addc_co_u32_e32 v45, vcc, 0, v139, vcc
	s_mov_b32 s1, 0xa00000
	v_cvt_pk_bf16_f32 v43, v46, v47
	global_store_dwordx4 v[44:45], v[40:43], off
	v_cvt_pk_bf16_f32 v32, v32, v33
	v_cvt_pk_bf16_f32 v33, v34, v35
	v_cvt_pk_bf16_f32 v34, v24, v25
	v_cvt_pk_bf16_f32 v35, v26, v27
	global_store_dwordx4 v[48:49], v[32:35], off offset:256
	s_mov_b64 s[20:21], 0xa00000
	v_cvt_pk_bf16_f32 v24, v36, v37
	v_cvt_pk_bf16_f32 v25, v38, v39
	v_cvt_pk_bf16_f32 v26, v28, v29
	v_add_co_u32_e32 v28, vcc, s1, v138
	v_lshl_add_u64 v[32:33], v[138:139], 0, s[20:21]
	s_nop 0
	v_addc_co_u32_e32 v29, vcc, 0, v139, vcc
	s_mov_b32 s1, 0xb00000
	v_cvt_pk_bf16_f32 v27, v30, v31
	global_store_dwordx4 v[28:29], v[24:27], off
	v_cvt_pk_bf16_f32 v16, v16, v17
	v_cvt_pk_bf16_f32 v17, v18, v19
	v_cvt_pk_bf16_f32 v18, v8, v9
	v_cvt_pk_bf16_f32 v19, v10, v11
	global_store_dwordx4 v[32:33], v[16:19], off offset:256
	v_cvt_pk_bf16_f32 v8, v20, v21
	v_cvt_pk_bf16_f32 v9, v22, v23
	v_cvt_pk_bf16_f32 v10, v12, v13
	v_add_co_u32_e32 v12, vcc, s1, v138
	s_mov_b64 s[20:21], 0xb00000
	s_nop 0
	v_addc_co_u32_e32 v13, vcc, 0, v139, vcc
	v_lshl_add_u64 v[16:17], v[138:139], 0, s[20:21]
	s_and_b64 vcc, exec, s[38:39]
	v_cvt_pk_bf16_f32 v11, v14, v15
	global_store_dwordx4 v[12:13], v[8:11], off
	v_cvt_pk_bf16_f32 v4, v4, v5
	v_cvt_pk_bf16_f32 v5, v6, v7
	v_cvt_pk_bf16_f32 v6, v0, v1
	v_cvt_pk_bf16_f32 v7, v2, v3
	global_store_dwordx4 v[16:17], v[4:7], off offset:256
	s_cbranch_vccz .LBB0_285
	s_waitcnt vmcnt(0)
	v_readlane_b32 s54, v253, 37
	s_cmpk_gt_u32 s3, 0xff
	v_readlane_b32 s55, v253, 38
	s_cbranch_scc1 .LBB0_296
	s_barrier
